# attention: staging loads at QK^T slots 4/12/20/28, issued ahead of the slot's K-fragment wait and MFMA
# baseline (speedup 1.0000x reference)
; __device__ __forceinline__ void partialSM(f32x16& p0, f32x16& p1, float mC) {
;   (void)mC; (void)p1;
;   for (int r = 0; r < 16; ++r) p0[r] = __builtin_amdgcn_exp2f(p0[r]);
; }
; __device__ __forceinline__ void finishSM(f32x16& p0, f32x16& p1, float& l_reg, bf16x8& pa0, bf16x8& pa1, bf16x8& pa2, bf16x8& pa3) {
;   for (int r = 0; r < 16; ++r) p1[r] = __builtin_amdgcn_exp2f(p1[r]);
;   float ps = 0; for (int r = 0; r < 16; ++r) ps += p0[r]; for (int r = 0; r < 16; ++r) ps += p1[r];
;   { auto rr = __builtin_amdgcn_permlane32_swap(__float_as_uint(ps), __float_as_uint(ps), false, false);
;     ps = __uint_as_float(rr[0]) + __uint_as_float(rr[1]); }
;   l_reg += ps;
;     ...
;   PK4(p0, 0, pa0); PK4(p0, 8, pa1); PK4(p1, 0, pa2); PK4(p1, 8, pa3);
;     ...
; }
; __device__ __forceinline__ void qkt(f32x16& p0, f32x16& p1, const bf16* Ks, const bf16x8* qr, int r32, int hi, const f32x16& negm) {
; #pragma unroll
;   for (int d0 = 0; d0 < 8; ++d0) { int cb = (d0 * 16 + hi * 8) * 2;
;     bf16x8 b0 = *reinterpret_cast<const bf16x8*>((const char*)Ks + KSWZ(r32, cb));
;     bf16x8 b1 = *reinterpret_cast<const bf16x8*>((const char*)Ks + KSWZ(32 + r32, cb));
;     if (d0 == 0) { p0 = __builtin_amdgcn_mfma_f32_32x32x16_bf16(b0, qr[0], negm, 0, 0, 0); p1 = __builtin_amdgcn_mfma_f32_32x32x16_bf16(b1, qr[0], negm, 0, 0, 0); }
;     else { p0 = __builtin_amdgcn_mfma_f32_32x32x16_bf16(b0, qr[d0], p0, 0, 0, 0); p1 = __builtin_amdgcn_mfma_f32_32x32x16_bf16(b1, qr[d0], p1, 0, 0, 0); } }
; }
; __device__ __forceinline__ int v_st(int k, int c) { const int kk = (k & ~0xC) | ((k & 4) << 1) | ((k & 8) >> 1); return ((kk >> 3) * 4 + (c >> 5)) * 512 + ((kk & 7) * 32 + (c & 31)) * 2; }
; __device__ __forceinline__ int v_rd_base(int lane) { return ((lane & 3) << 3) | (((lane >> 2) & 3) << 6) | (((lane >> 4) & 1) << 5) | (((lane >> 5) & 1) << 8); }
; template <int OFF> __device__ __forceinline__ s16x4 tr_read(int vb) {
;   s16x4 r; asm volatile("ds_read_b64_tr_b16 %0, %1 offset:%2" : "=&v"(r) : "v"(vb), "i"(OFF) : "memory"); return r;
; }
; template <int D0> __device__ __forceinline__ void pv_one(f32x16& od, int vb, bf16x8 pa0, bf16x8 pa1, bf16x8 pa2, bf16x8 pa3) {
;   const s16x4 l0 = tr_read<v_rd_off(D0, 0, 0)>(vb), h0 = tr_read<v_rd_off(D0, 0, 1)>(vb), l1 = tr_read<v_rd_off(D0, 1, 0)>(vb), h1 = tr_read<v_rd_off(D0, 1, 1)>(vb);
.Lattn_loop:
	s_barrier
	s_add_u32 s98, s98, 0x8000
	s_addc_u32 s99, s99, 0
	s_add_u32 s100, s100, 0x8000
	s_addc_u32 s101, s101, 0
	s_waitcnt lgkmcnt(3)
	v_mfma_f32_16x16x32_bf16 v[114:117], v[178:181], v[146:149], v[2:5]
	v_add_f32_e32 v250, v82, v250
	v_mfma_f32_16x16x32_bf16 v[118:121], v[178:181], v[162:165], v[2:5]
	ds_read_b128 v[178:181], v235 offset:16384
	v_add_f32_e32 v250, v83, v250
	v_add_f32_e32 v250, v84, v250
	s_waitcnt lgkmcnt(3)
	v_mfma_f32_16x16x32_bf16 v[122:125], v[182:185], v[146:149], v[2:5]
	v_add_f32_e32 v250, v85, v250
	v_mfma_f32_16x16x32_bf16 v[126:129], v[182:185], v[162:165], v[2:5]
	ds_read_b128 v[182:185], v235 offset:20480
	v_add_f32_e32 v250, v90, v250
	v_add_f32_e32 v250, v91, v250
	s_add_u32 m0, s79, 0
	s_nop 0
	global_load_lds_dwordx4 v246, s[98:99]
	s_waitcnt lgkmcnt(3)
	v_mfma_f32_16x16x32_bf16 v[130:133], v[186:189], v[146:149], v[2:5]
	v_add_f32_e32 v250, v92, v250
	v_mfma_f32_16x16x32_bf16 v[134:137], v[186:189], v[162:165], v[2:5]
	ds_read_b128 v[186:189], v235 offset:24576
	v_add_f32_e32 v250, v93, v250
	v_cvt_pk_bf16_f32 v82, v82, v83
	s_waitcnt lgkmcnt(3)
	v_mfma_f32_16x16x32_bf16 v[138:141], v[190:193], v[146:149], v[2:5]
	v_cvt_pk_bf16_f32 v83, v84, v85
	v_mfma_f32_16x16x32_bf16 v[142:145], v[190:193], v[162:165], v[2:5]
	ds_read_b128 v[190:193], v235 offset:28672
	v_cvt_pk_bf16_f32 v84, v90, v91
	v_cvt_pk_bf16_f32 v85, v92, v93
	s_waitcnt lgkmcnt(3)
	v_mfma_f32_16x16x32_bf16 v[114:117], v[178:181], v[150:153], v[114:117]
	v_add_f32_e32 v251, v86, v251
	v_mfma_f32_16x16x32_bf16 v[118:121], v[178:181], v[166:169], v[118:121]
	ds_read_b128 v[178:181], v236 offset:16384
	v_add_f32_e32 v251, v87, v251
	v_add_f32_e32 v251, v88, v251
	s_waitcnt lgkmcnt(3)
	v_mfma_f32_16x16x32_bf16 v[122:125], v[182:185], v[150:153], v[122:125]
	v_add_f32_e32 v251, v89, v251
	v_mfma_f32_16x16x32_bf16 v[126:129], v[182:185], v[166:169], v[126:129]
	ds_read_b128 v[182:185], v236 offset:20480
	v_add_f32_e32 v251, v94, v251
	v_add_f32_e32 v251, v95, v251
	s_add_u32 m0, s79, 1024
	s_nop 0
	global_load_lds_dwordx4 v247, s[98:99]
	s_waitcnt lgkmcnt(3)
	v_mfma_f32_16x16x32_bf16 v[130:133], v[186:189], v[150:153], v[130:133]
	v_add_f32_e32 v251, v96, v251
	v_mfma_f32_16x16x32_bf16 v[134:137], v[186:189], v[166:169], v[134:137]
	ds_read_b128 v[186:189], v236 offset:24576
	v_add_f32_e32 v251, v97, v251
	v_cvt_pk_bf16_f32 v86, v86, v87
	s_waitcnt lgkmcnt(3)
	v_mfma_f32_16x16x32_bf16 v[138:141], v[190:193], v[150:153], v[138:141]
	v_cvt_pk_bf16_f32 v87, v88, v89
	v_mfma_f32_16x16x32_bf16 v[142:145], v[190:193], v[166:169], v[142:145]
	ds_read_b128 v[190:193], v236 offset:28672
	v_cvt_pk_bf16_f32 v88, v94, v95
	v_cvt_pk_bf16_f32 v89, v96, v97
	s_waitcnt lgkmcnt(3)
	v_mfma_f32_16x16x32_bf16 v[114:117], v[178:181], v[154:157], v[114:117]
	v_add_f32_e32 v250, v98, v250
	v_mfma_f32_16x16x32_bf16 v[118:121], v[178:181], v[170:173], v[118:121]
	ds_read_b128 v[178:181], v237 offset:16384
	v_add_f32_e32 v250, v99, v250
	v_add_f32_e32 v250, v100, v250
	s_waitcnt lgkmcnt(3)
	v_mfma_f32_16x16x32_bf16 v[122:125], v[182:185], v[154:157], v[122:125]
	v_add_f32_e32 v250, v101, v250
	v_mfma_f32_16x16x32_bf16 v[126:129], v[182:185], v[170:173], v[126:129]
	ds_read_b128 v[182:185], v237 offset:20480
	v_add_f32_e32 v250, v106, v250
	v_add_f32_e32 v250, v107, v250
	s_add_u32 m0, s80, 49152
	s_nop 0
	global_load_lds_dwordx4 v248, s[100:101]
	s_waitcnt lgkmcnt(3)
	v_mfma_f32_16x16x32_bf16 v[130:133], v[186:189], v[154:157], v[130:133]
	v_add_f32_e32 v250, v108, v250
	ds_read_b64_tr_b16 v[202:203], v238 offset:0
	ds_read_b64_tr_b16 v[204:205], v238 offset:4096
	v_mfma_f32_16x16x32_bf16 v[134:137], v[186:189], v[170:173], v[134:137]
	ds_read_b128 v[186:189], v237 offset:24576
	v_add_f32_e32 v250, v109, v250
	v_cvt_pk_bf16_f32 v98, v98, v99
	s_waitcnt lgkmcnt(5)
	v_mfma_f32_16x16x32_bf16 v[138:141], v[190:193], v[154:157], v[138:141]
	v_cvt_pk_bf16_f32 v99, v100, v101
	ds_read_b64_tr_b16 v[206:207], v239 offset:0
	ds_read_b64_tr_b16 v[208:209], v239 offset:4096
	v_mfma_f32_16x16x32_bf16 v[142:145], v[190:193], v[170:173], v[142:145]
	ds_read_b128 v[190:193], v237 offset:28672
	v_cvt_pk_bf16_f32 v100, v106, v107
	v_cvt_pk_bf16_f32 v101, v108, v109
	s_waitcnt lgkmcnt(7)
	v_mfma_f32_16x16x32_bf16 v[114:117], v[178:181], v[158:161], v[114:117]
	v_add_f32_e32 v251, v102, v251
	ds_read_b64_tr_b16 v[210:211], v240 offset:0
	ds_read_b64_tr_b16 v[212:213], v240 offset:4096
	v_mfma_f32_16x16x32_bf16 v[118:121], v[178:181], v[174:177], v[118:121]
	v_add_f32_e32 v251, v103, v251
	v_add_f32_e32 v251, v104, v251
	s_waitcnt lgkmcnt(8)
	v_mfma_f32_16x16x32_bf16 v[122:125], v[182:185], v[158:161], v[122:125]
	v_add_f32_e32 v251, v105, v251
	ds_read_b64_tr_b16 v[214:215], v241 offset:0
	ds_read_b64_tr_b16 v[216:217], v241 offset:4096
	v_mfma_f32_16x16x32_bf16 v[126:129], v[182:185], v[174:177], v[126:129]
	v_add_f32_e32 v251, v110, v251
	v_add_f32_e32 v251, v111, v251
	s_add_u32 m0, s80, 50176
	s_nop 0
	global_load_lds_dwordx4 v249, s[100:101]
	s_waitcnt lgkmcnt(7)
	v_mfma_f32_16x16x32_bf16 v[130:133], v[186:189], v[158:161], v[130:133]
	v_add_f32_e32 v251, v112, v251
	ds_read_b64_tr_b16 v[218:219], v242 offset:0
	ds_read_b64_tr_b16 v[220:221], v242 offset:4096
	v_mfma_f32_16x16x32_bf16 v[134:137], v[186:189], v[174:177], v[134:137]
	v_add_f32_e32 v251, v113, v251
	v_cvt_pk_bf16_f32 v102, v102, v103
	s_waitcnt lgkmcnt(6)
; __device__ __forceinline__ void partialSM(f32x16& p0, f32x16& p1, float mC) {
;   (void)mC; (void)p1;
;   for (int r = 0; r < 16; ++r) p0[r] = __builtin_amdgcn_exp2f(p0[r]);
; }
; __device__ __forceinline__ void finishSM(f32x16& p0, f32x16& p1, float& l_reg, bf16x8& pa0, bf16x8& pa1, bf16x8& pa2, bf16x8& pa3) {
;   for (int r = 0; r < 16; ++r) p1[r] = __builtin_amdgcn_exp2f(p1[r]);
;   float ps = 0; for (int r = 0; r < 16; ++r) ps += p0[r]; for (int r = 0; r < 16; ++r) ps += p1[r];
;   { auto rr = __builtin_amdgcn_permlane32_swap(__float_as_uint(ps), __float_as_uint(ps), false, false);
;     ps = __uint_as_float(rr[0]) + __uint_as_float(rr[1]); }
;   l_reg += ps;
;     ...
;   PK4(p0, 0, pa0); PK4(p0, 8, pa1); PK4(p1, 0, pa2); PK4(p1, 8, pa3);
;     ...
; }
; __device__ __forceinline__ void qkt(f32x16& p0, f32x16& p1, const bf16* Ks, const bf16x8* qr, int r32, int hi, const f32x16& negm) {
; #pragma unroll
;   for (int d0 = 0; d0 < 8; ++d0) { int cb = (d0 * 16 + hi * 8) * 2;
;     bf16x8 b0 = *reinterpret_cast<const bf16x8*>((const char*)Ks + KSWZ(r32, cb));
;     bf16x8 b1 = *reinterpret_cast<const bf16x8*>((const char*)Ks + KSWZ(32 + r32, cb));
;     if (d0 == 0) { p0 = __builtin_amdgcn_mfma_f32_32x32x16_bf16(b0, qr[0], negm, 0, 0, 0); p1 = __builtin_amdgcn_mfma_f32_32x32x16_bf16(b1, qr[0], negm, 0, 0, 0); }
;     else { p0 = __builtin_amdgcn_mfma_f32_32x32x16_bf16(b0, qr[d0], p0, 0, 0, 0); p1 = __builtin_amdgcn_mfma_f32_32x32x16_bf16(b1, qr[d0], p1, 0, 0, 0); } }
; }
; __device__ __forceinline__ int v_st(int k, int c) { const int kk = (k & ~0xC) | ((k & 4) << 1) | ((k & 8) >> 1); return ((kk >> 3) * 4 + (c >> 5)) * 512 + ((kk & 7) * 32 + (c & 31)) * 2; }
; __device__ __forceinline__ int v_rd_base(int lane) { return ((lane & 3) << 3) | (((lane >> 2) & 3) << 6) | (((lane >> 4) & 1) << 5) | (((lane >> 5) & 1) << 8); }
; template <int OFF> __device__ __forceinline__ s16x4 tr_read(int vb) {
;   s16x4 r; asm volatile("ds_read_b64_tr_b16 %0, %1 offset:%2" : "=&v"(r) : "v"(vb), "i"(OFF) : "memory"); return r;
; }
; template <int D0> __device__ __forceinline__ void pv_one(f32x16& od, int vb, bf16x8 pa0, bf16x8 pa1, bf16x8 pa2, bf16x8 pa3) {
;   const s16x4 l0 = tr_read<v_rd_off(D0, 0, 0)>(vb), h0 = tr_read<v_rd_off(D0, 0, 1)>(vb), l1 = tr_read<v_rd_off(D0, 1, 0)>(vb), h1 = tr_read<v_rd_off(D0, 1, 1)>(vb);
	v_mfma_f32_16x16x32_bf16 v[138:141], v[190:193], v[158:161], v[138:141]
	v_cvt_pk_bf16_f32 v103, v104, v105
	ds_read_b64_tr_b16 v[222:223], v243 offset:0
	ds_read_b64_tr_b16 v[224:225], v243 offset:4096
	v_mfma_f32_16x16x32_bf16 v[142:145], v[190:193], v[174:177], v[142:145]
	v_cvt_pk_bf16_f32 v104, v110, v111
	v_cvt_pk_bf16_f32 v105, v112, v113
	v_mfma_f32_16x16x32_bf16 v[18:21], v[202:205], v[82:85], v[18:21]
	v_exp_f32_e32 v114, v114
	v_mfma_f32_16x16x32_bf16 v[22:25], v[202:205], v[86:89], v[22:25]
	ds_read_b64_tr_b16 v[202:203], v244 offset:0
	ds_read_b64_tr_b16 v[204:205], v244 offset:4096
	v_exp_f32_e32 v115, v115
	v_mfma_f32_16x16x32_bf16 v[26:29], v[206:209], v[82:85], v[26:29]
	v_exp_f32_e32 v116, v116
	v_mfma_f32_16x16x32_bf16 v[30:33], v[206:209], v[86:89], v[30:33]
	ds_read_b64_tr_b16 v[206:207], v245 offset:0
	ds_read_b64_tr_b16 v[208:209], v245 offset:4096
	v_exp_f32_e32 v117, v117
	s_waitcnt lgkmcnt(10)
	v_mfma_f32_16x16x32_bf16 v[34:37], v[210:213], v[82:85], v[34:37]
	v_exp_f32_e32 v118, v118
	v_mfma_f32_16x16x32_bf16 v[38:41], v[210:213], v[86:89], v[38:41]
	ds_read_b64_tr_b16 v[210:211], v238 offset:8192
	ds_read_b64_tr_b16 v[212:213], v238 offset:12288
	v_exp_f32_e32 v119, v119
	s_waitcnt lgkmcnt(10)
	v_mfma_f32_16x16x32_bf16 v[42:45], v[214:217], v[82:85], v[42:45]
	v_exp_f32_e32 v120, v120
	v_mfma_f32_16x16x32_bf16 v[46:49], v[214:217], v[86:89], v[46:49]
	ds_read_b64_tr_b16 v[214:215], v239 offset:8192
	ds_read_b64_tr_b16 v[216:217], v239 offset:12288
	v_exp_f32_e32 v121, v121
	s_waitcnt lgkmcnt(10)
	v_mfma_f32_16x16x32_bf16 v[50:53], v[218:221], v[82:85], v[50:53]
	v_exp_f32_e32 v122, v122
	v_mfma_f32_16x16x32_bf16 v[54:57], v[218:221], v[86:89], v[54:57]
	ds_read_b64_tr_b16 v[218:219], v240 offset:8192
	ds_read_b64_tr_b16 v[220:221], v240 offset:12288
	v_exp_f32_e32 v123, v123
	s_waitcnt lgkmcnt(10)
	v_mfma_f32_16x16x32_bf16 v[58:61], v[222:225], v[82:85], v[58:61]
	v_exp_f32_e32 v124, v124
	v_mfma_f32_16x16x32_bf16 v[62:65], v[222:225], v[86:89], v[62:65]
	ds_read_b64_tr_b16 v[222:223], v241 offset:8192
	ds_read_b64_tr_b16 v[224:225], v241 offset:12288
	v_exp_f32_e32 v125, v125
	s_waitcnt lgkmcnt(10)
	v_mfma_f32_16x16x32_bf16 v[66:69], v[202:205], v[82:85], v[66:69]
	v_exp_f32_e32 v126, v126
	v_mfma_f32_16x16x32_bf16 v[70:73], v[202:205], v[86:89], v[70:73]
	ds_read_b64_tr_b16 v[202:203], v242 offset:8192
	ds_read_b64_tr_b16 v[204:205], v242 offset:12288
	v_exp_f32_e32 v127, v127
	s_waitcnt lgkmcnt(10)
	v_mfma_f32_16x16x32_bf16 v[74:77], v[206:209], v[82:85], v[74:77]
	v_exp_f32_e32 v128, v128
	v_mfma_f32_16x16x32_bf16 v[78:81], v[206:209], v[86:89], v[78:81]
	ds_read_b64_tr_b16 v[206:207], v243 offset:8192
	ds_read_b64_tr_b16 v[208:209], v243 offset:12288
	v_exp_f32_e32 v129, v129
	s_waitcnt lgkmcnt(10)
	v_mfma_f32_16x16x32_bf16 v[18:21], v[210:213], v[98:101], v[18:21]
	v_exp_f32_e32 v130, v130
	v_mfma_f32_16x16x32_bf16 v[22:25], v[210:213], v[102:105], v[22:25]
	ds_read_b64_tr_b16 v[210:211], v244 offset:8192
	ds_read_b64_tr_b16 v[212:213], v244 offset:12288
	v_exp_f32_e32 v131, v131
	s_waitcnt lgkmcnt(10)
	v_mfma_f32_16x16x32_bf16 v[26:29], v[214:217], v[98:101], v[26:29]
	v_exp_f32_e32 v132, v132
	v_mfma_f32_16x16x32_bf16 v[30:33], v[214:217], v[102:105], v[30:33]
	ds_read_b64_tr_b16 v[214:215], v245 offset:8192
	ds_read_b64_tr_b16 v[216:217], v245 offset:12288
	v_exp_f32_e32 v133, v133
	s_waitcnt lgkmcnt(10)
	v_mfma_f32_16x16x32_bf16 v[34:37], v[218:221], v[98:101], v[34:37]
	v_exp_f32_e32 v134, v134
	v_mfma_f32_16x16x32_bf16 v[38:41], v[218:221], v[102:105], v[38:41]
	v_exp_f32_e32 v135, v135
	s_waitcnt lgkmcnt(8)
	v_mfma_f32_16x16x32_bf16 v[42:45], v[222:225], v[98:101], v[42:45]
	v_exp_f32_e32 v136, v136
	v_mfma_f32_16x16x32_bf16 v[46:49], v[222:225], v[102:105], v[46:49]
	v_exp_f32_e32 v137, v137
	s_waitcnt lgkmcnt(6)
	v_mfma_f32_16x16x32_bf16 v[50:53], v[202:205], v[98:101], v[50:53]
	v_exp_f32_e32 v138, v138
	ds_read_b128 v[178:181], v234 offset:32768
	v_mfma_f32_16x16x32_bf16 v[54:57], v[202:205], v[102:105], v[54:57]
	v_exp_f32_e32 v139, v139
	s_waitcnt lgkmcnt(5)
	v_mfma_f32_16x16x32_bf16 v[58:61], v[206:209], v[98:101], v[58:61]
	v_exp_f32_e32 v140, v140
	ds_read_b128 v[182:185], v234 offset:36864
	v_mfma_f32_16x16x32_bf16 v[62:65], v[206:209], v[102:105], v[62:65]
	v_exp_f32_e32 v141, v141
	s_waitcnt lgkmcnt(4)
	v_mfma_f32_16x16x32_bf16 v[66:69], v[210:213], v[98:101], v[66:69]
	v_exp_f32_e32 v142, v142
	ds_read_b128 v[186:189], v234 offset:40960
	v_mfma_f32_16x16x32_bf16 v[70:73], v[210:213], v[102:105], v[70:73]
	v_exp_f32_e32 v143, v143
	s_waitcnt lgkmcnt(3)
	v_mfma_f32_16x16x32_bf16 v[74:77], v[214:217], v[98:101], v[74:77]
	v_exp_f32_e32 v144, v144
	ds_read_b128 v[190:193], v234 offset:45056
	v_mfma_f32_16x16x32_bf16 v[78:81], v[214:217], v[102:105], v[78:81]
	v_exp_f32_e32 v145, v145
	s_waitcnt vmcnt(4)
	s_barrier
; __device__ __forceinline__ void partialSM(f32x16& p0, f32x16& p1, float mC) {
;   (void)mC; (void)p1;
;   for (int r = 0; r < 16; ++r) p0[r] = __builtin_amdgcn_exp2f(p0[r]);
; }
; __device__ __forceinline__ void finishSM(f32x16& p0, f32x16& p1, float& l_reg, bf16x8& pa0, bf16x8& pa1, bf16x8& pa2, bf16x8& pa3) {
;   for (int r = 0; r < 16; ++r) p1[r] = __builtin_amdgcn_exp2f(p1[r]);
;   float ps = 0; for (int r = 0; r < 16; ++r) ps += p0[r]; for (int r = 0; r < 16; ++r) ps += p1[r];
;   { auto rr = __builtin_amdgcn_permlane32_swap(__float_as_uint(ps), __float_as_uint(ps), false, false);
;     ps = __uint_as_float(rr[0]) + __uint_as_float(rr[1]); }
;   l_reg += ps;
;     ...
;   PK4(p0, 0, pa0); PK4(p0, 8, pa1); PK4(p1, 0, pa2); PK4(p1, 8, pa3);
;     ...
; }
; __device__ __forceinline__ void qkt(f32x16& p0, f32x16& p1, const bf16* Ks, const bf16x8* qr, int r32, int hi, const f32x16& negm) {
; #pragma unroll
;   for (int d0 = 0; d0 < 8; ++d0) { int cb = (d0 * 16 + hi * 8) * 2;
;     bf16x8 b0 = *reinterpret_cast<const bf16x8*>((const char*)Ks + KSWZ(r32, cb));
;     bf16x8 b1 = *reinterpret_cast<const bf16x8*>((const char*)Ks + KSWZ(32 + r32, cb));
;     if (d0 == 0) { p0 = __builtin_amdgcn_mfma_f32_32x32x16_bf16(b0, qr[0], negm, 0, 0, 0); p1 = __builtin_amdgcn_mfma_f32_32x32x16_bf16(b1, qr[0], negm, 0, 0, 0); }
;     else { p0 = __builtin_amdgcn_mfma_f32_32x32x16_bf16(b0, qr[d0], p0, 0, 0, 0); p1 = __builtin_amdgcn_mfma_f32_32x32x16_bf16(b1, qr[d0], p1, 0, 0, 0); } }
; }
; __device__ __forceinline__ int v_st(int k, int c) { const int kk = (k & ~0xC) | ((k & 4) << 1) | ((k & 8) >> 1); return ((kk >> 3) * 4 + (c >> 5)) * 512 + ((kk & 7) * 32 + (c & 31)) * 2; }
; __device__ __forceinline__ int v_rd_base(int lane) { return ((lane & 3) << 3) | (((lane >> 2) & 3) << 6) | (((lane >> 4) & 1) << 5) | (((lane >> 5) & 1) << 8); }
; template <int OFF> __device__ __forceinline__ s16x4 tr_read(int vb) {
;   s16x4 r; asm volatile("ds_read_b64_tr_b16 %0, %1 offset:%2" : "=&v"(r) : "v"(vb), "i"(OFF) : "memory"); return r;
; }
; template <int D0> __device__ __forceinline__ void pv_one(f32x16& od, int vb, bf16x8 pa0, bf16x8 pa1, bf16x8 pa2, bf16x8 pa3) {
;   const s16x4 l0 = tr_read<v_rd_off(D0, 0, 0)>(vb), h0 = tr_read<v_rd_off(D0, 0, 1)>(vb), l1 = tr_read<v_rd_off(D0, 1, 0)>(vb), h1 = tr_read<v_rd_off(D0, 1, 1)>(vb);
	s_add_u32 s98, s98, 0x8000
	s_addc_u32 s99, s99, 0
	s_add_u32 s100, s100, 0x8000
	s_addc_u32 s101, s101, 0
	s_waitcnt lgkmcnt(3)
	v_mfma_f32_16x16x32_bf16 v[82:85], v[178:181], v[146:149], v[2:5]
	v_add_f32_e32 v250, v114, v250
	v_mfma_f32_16x16x32_bf16 v[86:89], v[178:181], v[162:165], v[2:5]
	ds_read_b128 v[178:181], v235 offset:32768
	v_add_f32_e32 v250, v115, v250
	v_add_f32_e32 v250, v116, v250
	s_waitcnt lgkmcnt(3)
	v_mfma_f32_16x16x32_bf16 v[90:93], v[182:185], v[146:149], v[2:5]
	v_add_f32_e32 v250, v117, v250
	v_mfma_f32_16x16x32_bf16 v[94:97], v[182:185], v[162:165], v[2:5]
	ds_read_b128 v[182:185], v235 offset:36864
	v_add_f32_e32 v250, v122, v250
	v_add_f32_e32 v250, v123, v250
	s_add_u32 m0, s79, 16384
	s_nop 0
	global_load_lds_dwordx4 v246, s[98:99]
	s_waitcnt lgkmcnt(3)
	v_mfma_f32_16x16x32_bf16 v[98:101], v[186:189], v[146:149], v[2:5]
	v_add_f32_e32 v250, v124, v250
	v_mfma_f32_16x16x32_bf16 v[102:105], v[186:189], v[162:165], v[2:5]
	ds_read_b128 v[186:189], v235 offset:40960
	v_add_f32_e32 v250, v125, v250
	v_cvt_pk_bf16_f32 v114, v114, v115
	s_waitcnt lgkmcnt(3)
	v_mfma_f32_16x16x32_bf16 v[106:109], v[190:193], v[146:149], v[2:5]
	v_cvt_pk_bf16_f32 v115, v116, v117
	v_mfma_f32_16x16x32_bf16 v[110:113], v[190:193], v[162:165], v[2:5]
	ds_read_b128 v[190:193], v235 offset:45056
	v_cvt_pk_bf16_f32 v116, v122, v123
	v_cvt_pk_bf16_f32 v117, v124, v125
	s_waitcnt lgkmcnt(3)
	v_mfma_f32_16x16x32_bf16 v[82:85], v[178:181], v[150:153], v[82:85]
	v_add_f32_e32 v251, v118, v251
	v_mfma_f32_16x16x32_bf16 v[86:89], v[178:181], v[166:169], v[86:89]
	ds_read_b128 v[178:181], v236 offset:32768
	v_add_f32_e32 v251, v119, v251
	v_add_f32_e32 v251, v120, v251
	s_waitcnt lgkmcnt(3)
	v_mfma_f32_16x16x32_bf16 v[90:93], v[182:185], v[150:153], v[90:93]
	v_add_f32_e32 v251, v121, v251
	v_mfma_f32_16x16x32_bf16 v[94:97], v[182:185], v[166:169], v[94:97]
	ds_read_b128 v[182:185], v236 offset:36864
	v_add_f32_e32 v251, v126, v251
	v_add_f32_e32 v251, v127, v251
	s_add_u32 m0, s79, 17408
	s_nop 0
	global_load_lds_dwordx4 v247, s[98:99]
	s_waitcnt lgkmcnt(3)
	v_mfma_f32_16x16x32_bf16 v[98:101], v[186:189], v[150:153], v[98:101]
	v_add_f32_e32 v251, v128, v251
	v_mfma_f32_16x16x32_bf16 v[102:105], v[186:189], v[166:169], v[102:105]
	ds_read_b128 v[186:189], v236 offset:40960
	v_add_f32_e32 v251, v129, v251
	v_cvt_pk_bf16_f32 v118, v118, v119
	s_waitcnt lgkmcnt(3)
	v_mfma_f32_16x16x32_bf16 v[106:109], v[190:193], v[150:153], v[106:109]
	v_cvt_pk_bf16_f32 v119, v120, v121
	v_mfma_f32_16x16x32_bf16 v[110:113], v[190:193], v[166:169], v[110:113]
	ds_read_b128 v[190:193], v236 offset:45056
	v_cvt_pk_bf16_f32 v120, v126, v127
	v_cvt_pk_bf16_f32 v121, v128, v129
	s_waitcnt lgkmcnt(3)
	v_mfma_f32_16x16x32_bf16 v[82:85], v[178:181], v[154:157], v[82:85]
	v_add_f32_e32 v250, v130, v250
	v_mfma_f32_16x16x32_bf16 v[86:89], v[178:181], v[170:173], v[86:89]
	ds_read_b128 v[178:181], v237 offset:32768
	v_add_f32_e32 v250, v131, v250
	v_add_f32_e32 v250, v132, v250
	s_waitcnt lgkmcnt(3)
	v_mfma_f32_16x16x32_bf16 v[90:93], v[182:185], v[154:157], v[90:93]
	v_add_f32_e32 v250, v133, v250
	v_mfma_f32_16x16x32_bf16 v[94:97], v[182:185], v[170:173], v[94:97]
	ds_read_b128 v[182:185], v237 offset:36864
	v_add_f32_e32 v250, v138, v250
	v_add_f32_e32 v250, v139, v250
	s_add_u32 m0, s80, 0
	s_nop 0
	global_load_lds_dwordx4 v248, s[100:101]
	s_waitcnt lgkmcnt(3)
	v_mfma_f32_16x16x32_bf16 v[98:101], v[186:189], v[154:157], v[98:101]
	v_add_f32_e32 v250, v140, v250
	ds_read_b64_tr_b16 v[202:203], v238 offset:16384
	ds_read_b64_tr_b16 v[204:205], v238 offset:20480
	v_mfma_f32_16x16x32_bf16 v[102:105], v[186:189], v[170:173], v[102:105]
	ds_read_b128 v[186:189], v237 offset:40960
	v_add_f32_e32 v250, v141, v250
	v_cvt_pk_bf16_f32 v130, v130, v131
	s_waitcnt lgkmcnt(5)
	v_mfma_f32_16x16x32_bf16 v[106:109], v[190:193], v[154:157], v[106:109]
	v_cvt_pk_bf16_f32 v131, v132, v133
	ds_read_b64_tr_b16 v[206:207], v239 offset:16384
	ds_read_b64_tr_b16 v[208:209], v239 offset:20480
	v_mfma_f32_16x16x32_bf16 v[110:113], v[190:193], v[170:173], v[110:113]
	ds_read_b128 v[190:193], v237 offset:45056
	v_cvt_pk_bf16_f32 v132, v138, v139
	v_cvt_pk_bf16_f32 v133, v140, v141
	s_waitcnt lgkmcnt(7)
	v_mfma_f32_16x16x32_bf16 v[82:85], v[178:181], v[158:161], v[82:85]
	v_add_f32_e32 v251, v134, v251
	ds_read_b64_tr_b16 v[210:211], v240 offset:16384
	ds_read_b64_tr_b16 v[212:213], v240 offset:20480
	v_mfma_f32_16x16x32_bf16 v[86:89], v[178:181], v[174:177], v[86:89]
	v_add_f32_e32 v251, v135, v251
	v_add_f32_e32 v251, v136, v251
	s_waitcnt lgkmcnt(8)
	v_mfma_f32_16x16x32_bf16 v[90:93], v[182:185], v[158:161], v[90:93]
	v_add_f32_e32 v251, v137, v251
	ds_read_b64_tr_b16 v[214:215], v241 offset:16384
	ds_read_b64_tr_b16 v[216:217], v241 offset:20480
	v_mfma_f32_16x16x32_bf16 v[94:97], v[182:185], v[174:177], v[94:97]
	v_add_f32_e32 v251, v142, v251
	v_add_f32_e32 v251, v143, v251
	s_add_u32 m0, s80, 1024
	s_nop 0
	global_load_lds_dwordx4 v249, s[100:101]
	s_waitcnt lgkmcnt(7)
	v_mfma_f32_16x16x32_bf16 v[98:101], v[186:189], v[158:161], v[98:101]
	v_add_f32_e32 v251, v144, v251
	ds_read_b64_tr_b16 v[218:219], v242 offset:16384
	ds_read_b64_tr_b16 v[220:221], v242 offset:20480
	v_mfma_f32_16x16x32_bf16 v[102:105], v[186:189], v[174:177], v[102:105]
	v_add_f32_e32 v251, v145, v251
	v_cvt_pk_bf16_f32 v134, v134, v135
	s_waitcnt lgkmcnt(6)
; __device__ __forceinline__ void partialSM(f32x16& p0, f32x16& p1, float mC) {
;   (void)mC; (void)p1;
;   for (int r = 0; r < 16; ++r) p0[r] = __builtin_amdgcn_exp2f(p0[r]);
; }
; __device__ __forceinline__ void finishSM(f32x16& p0, f32x16& p1, float& l_reg, bf16x8& pa0, bf16x8& pa1, bf16x8& pa2, bf16x8& pa3) {
;   for (int r = 0; r < 16; ++r) p1[r] = __builtin_amdgcn_exp2f(p1[r]);
;   float ps = 0; for (int r = 0; r < 16; ++r) ps += p0[r]; for (int r = 0; r < 16; ++r) ps += p1[r];
;   { auto rr = __builtin_amdgcn_permlane32_swap(__float_as_uint(ps), __float_as_uint(ps), false, false);
;     ps = __uint_as_float(rr[0]) + __uint_as_float(rr[1]); }
;   l_reg += ps;
;     ...
;   PK4(p0, 0, pa0); PK4(p0, 8, pa1); PK4(p1, 0, pa2); PK4(p1, 8, pa3);
;     ...
; }
; __device__ __forceinline__ void qkt(f32x16& p0, f32x16& p1, const bf16* Ks, const bf16x8* qr, int r32, int hi, const f32x16& negm) {
; #pragma unroll
;   for (int d0 = 0; d0 < 8; ++d0) { int cb = (d0 * 16 + hi * 8) * 2;
;     bf16x8 b0 = *reinterpret_cast<const bf16x8*>((const char*)Ks + KSWZ(r32, cb));
;     bf16x8 b1 = *reinterpret_cast<const bf16x8*>((const char*)Ks + KSWZ(32 + r32, cb));
;     if (d0 == 0) { p0 = __builtin_amdgcn_mfma_f32_32x32x16_bf16(b0, qr[0], negm, 0, 0, 0); p1 = __builtin_amdgcn_mfma_f32_32x32x16_bf16(b1, qr[0], negm, 0, 0, 0); }
;     else { p0 = __builtin_amdgcn_mfma_f32_32x32x16_bf16(b0, qr[d0], p0, 0, 0, 0); p1 = __builtin_amdgcn_mfma_f32_32x32x16_bf16(b1, qr[d0], p1, 0, 0, 0); } }
; }
; __device__ __forceinline__ int v_st(int k, int c) { const int kk = (k & ~0xC) | ((k & 4) << 1) | ((k & 8) >> 1); return ((kk >> 3) * 4 + (c >> 5)) * 512 + ((kk & 7) * 32 + (c & 31)) * 2; }
; __device__ __forceinline__ int v_rd_base(int lane) { return ((lane & 3) << 3) | (((lane >> 2) & 3) << 6) | (((lane >> 4) & 1) << 5) | (((lane >> 5) & 1) << 8); }
; template <int OFF> __device__ __forceinline__ s16x4 tr_read(int vb) {
;   s16x4 r; asm volatile("ds_read_b64_tr_b16 %0, %1 offset:%2" : "=&v"(r) : "v"(vb), "i"(OFF) : "memory"); return r;
; }
; template <int D0> __device__ __forceinline__ void pv_one(f32x16& od, int vb, bf16x8 pa0, bf16x8 pa1, bf16x8 pa2, bf16x8 pa3) {
;   const s16x4 l0 = tr_read<v_rd_off(D0, 0, 0)>(vb), h0 = tr_read<v_rd_off(D0, 0, 1)>(vb), l1 = tr_read<v_rd_off(D0, 1, 0)>(vb), h1 = tr_read<v_rd_off(D0, 1, 1)>(vb);
	v_mfma_f32_16x16x32_bf16 v[106:109], v[190:193], v[158:161], v[106:109]
	v_cvt_pk_bf16_f32 v135, v136, v137
	ds_read_b64_tr_b16 v[222:223], v243 offset:16384
	ds_read_b64_tr_b16 v[224:225], v243 offset:20480
	v_mfma_f32_16x16x32_bf16 v[110:113], v[190:193], v[174:177], v[110:113]
	v_cvt_pk_bf16_f32 v136, v142, v143
	v_cvt_pk_bf16_f32 v137, v144, v145
	v_mfma_f32_16x16x32_bf16 v[18:21], v[202:205], v[114:117], v[18:21]
	v_exp_f32_e32 v82, v82
	v_mfma_f32_16x16x32_bf16 v[22:25], v[202:205], v[118:121], v[22:25]
	ds_read_b64_tr_b16 v[202:203], v244 offset:16384
	ds_read_b64_tr_b16 v[204:205], v244 offset:20480
	v_exp_f32_e32 v83, v83
	v_mfma_f32_16x16x32_bf16 v[26:29], v[206:209], v[114:117], v[26:29]
	v_exp_f32_e32 v84, v84
	v_mfma_f32_16x16x32_bf16 v[30:33], v[206:209], v[118:121], v[30:33]
	ds_read_b64_tr_b16 v[206:207], v245 offset:16384
	ds_read_b64_tr_b16 v[208:209], v245 offset:20480
	v_exp_f32_e32 v85, v85
	s_waitcnt lgkmcnt(10)
	v_mfma_f32_16x16x32_bf16 v[34:37], v[210:213], v[114:117], v[34:37]
	v_exp_f32_e32 v86, v86
	v_mfma_f32_16x16x32_bf16 v[38:41], v[210:213], v[118:121], v[38:41]
	ds_read_b64_tr_b16 v[210:211], v238 offset:24576
	ds_read_b64_tr_b16 v[212:213], v238 offset:28672
	v_exp_f32_e32 v87, v87
	s_waitcnt lgkmcnt(10)
	v_mfma_f32_16x16x32_bf16 v[42:45], v[214:217], v[114:117], v[42:45]
	v_exp_f32_e32 v88, v88
	v_mfma_f32_16x16x32_bf16 v[46:49], v[214:217], v[118:121], v[46:49]
	ds_read_b64_tr_b16 v[214:215], v239 offset:24576
	ds_read_b64_tr_b16 v[216:217], v239 offset:28672
	v_exp_f32_e32 v89, v89
	s_waitcnt lgkmcnt(10)
	v_mfma_f32_16x16x32_bf16 v[50:53], v[218:221], v[114:117], v[50:53]
	v_exp_f32_e32 v90, v90
	v_mfma_f32_16x16x32_bf16 v[54:57], v[218:221], v[118:121], v[54:57]
	ds_read_b64_tr_b16 v[218:219], v240 offset:24576
	ds_read_b64_tr_b16 v[220:221], v240 offset:28672
	v_exp_f32_e32 v91, v91
	s_waitcnt lgkmcnt(10)
	v_mfma_f32_16x16x32_bf16 v[58:61], v[222:225], v[114:117], v[58:61]
	v_exp_f32_e32 v92, v92
	v_mfma_f32_16x16x32_bf16 v[62:65], v[222:225], v[118:121], v[62:65]
	ds_read_b64_tr_b16 v[222:223], v241 offset:24576
	ds_read_b64_tr_b16 v[224:225], v241 offset:28672
	v_exp_f32_e32 v93, v93
	s_waitcnt lgkmcnt(10)
	v_mfma_f32_16x16x32_bf16 v[66:69], v[202:205], v[114:117], v[66:69]
	v_exp_f32_e32 v94, v94
	v_mfma_f32_16x16x32_bf16 v[70:73], v[202:205], v[118:121], v[70:73]
	ds_read_b64_tr_b16 v[202:203], v242 offset:24576
	ds_read_b64_tr_b16 v[204:205], v242 offset:28672
	v_exp_f32_e32 v95, v95
	s_waitcnt lgkmcnt(10)
	v_mfma_f32_16x16x32_bf16 v[74:77], v[206:209], v[114:117], v[74:77]
	v_exp_f32_e32 v96, v96
	v_mfma_f32_16x16x32_bf16 v[78:81], v[206:209], v[118:121], v[78:81]
	ds_read_b64_tr_b16 v[206:207], v243 offset:24576
	ds_read_b64_tr_b16 v[208:209], v243 offset:28672
	v_exp_f32_e32 v97, v97
	s_waitcnt lgkmcnt(10)
	v_mfma_f32_16x16x32_bf16 v[18:21], v[210:213], v[130:133], v[18:21]
	v_exp_f32_e32 v98, v98
	v_mfma_f32_16x16x32_bf16 v[22:25], v[210:213], v[134:137], v[22:25]
	ds_read_b64_tr_b16 v[210:211], v244 offset:24576
	ds_read_b64_tr_b16 v[212:213], v244 offset:28672
	v_exp_f32_e32 v99, v99
	s_waitcnt lgkmcnt(10)
	v_mfma_f32_16x16x32_bf16 v[26:29], v[214:217], v[130:133], v[26:29]
	v_exp_f32_e32 v100, v100
	v_mfma_f32_16x16x32_bf16 v[30:33], v[214:217], v[134:137], v[30:33]
	ds_read_b64_tr_b16 v[214:215], v245 offset:24576
	ds_read_b64_tr_b16 v[216:217], v245 offset:28672
	v_exp_f32_e32 v101, v101
	s_waitcnt lgkmcnt(10)
	v_mfma_f32_16x16x32_bf16 v[34:37], v[218:221], v[130:133], v[34:37]
	v_exp_f32_e32 v102, v102
	v_mfma_f32_16x16x32_bf16 v[38:41], v[218:221], v[134:137], v[38:41]
	v_exp_f32_e32 v103, v103
	s_waitcnt lgkmcnt(8)
	v_mfma_f32_16x16x32_bf16 v[42:45], v[222:225], v[130:133], v[42:45]
	v_exp_f32_e32 v104, v104
	v_mfma_f32_16x16x32_bf16 v[46:49], v[222:225], v[134:137], v[46:49]
	v_exp_f32_e32 v105, v105
	s_waitcnt lgkmcnt(6)
	v_mfma_f32_16x16x32_bf16 v[50:53], v[202:205], v[130:133], v[50:53]
	v_exp_f32_e32 v106, v106
	ds_read_b128 v[178:181], v234 offset:49152
	v_mfma_f32_16x16x32_bf16 v[54:57], v[202:205], v[134:137], v[54:57]
	v_exp_f32_e32 v107, v107
	s_waitcnt lgkmcnt(5)
	v_mfma_f32_16x16x32_bf16 v[58:61], v[206:209], v[130:133], v[58:61]
	v_exp_f32_e32 v108, v108
	ds_read_b128 v[182:185], v234 offset:53248
	v_mfma_f32_16x16x32_bf16 v[62:65], v[206:209], v[134:137], v[62:65]
	v_exp_f32_e32 v109, v109
	s_waitcnt lgkmcnt(4)
	v_mfma_f32_16x16x32_bf16 v[66:69], v[210:213], v[130:133], v[66:69]
	v_exp_f32_e32 v110, v110
	ds_read_b128 v[186:189], v234 offset:57344
	v_mfma_f32_16x16x32_bf16 v[70:73], v[210:213], v[134:137], v[70:73]
	v_exp_f32_e32 v111, v111
	s_waitcnt lgkmcnt(3)
	v_mfma_f32_16x16x32_bf16 v[74:77], v[214:217], v[130:133], v[74:77]
	v_exp_f32_e32 v112, v112
	ds_read_b128 v[190:193], v234 offset:61440
	v_mfma_f32_16x16x32_bf16 v[78:81], v[214:217], v[134:137], v[78:81]
	v_exp_f32_e32 v113, v113
	s_waitcnt vmcnt(4)
	s_barrier
; __device__ __forceinline__ void partialSM(f32x16& p0, f32x16& p1, float mC) {
;   (void)mC; (void)p1;
;   for (int r = 0; r < 16; ++r) p0[r] = __builtin_amdgcn_exp2f(p0[r]);
; }
; __device__ __forceinline__ void finishSM(f32x16& p0, f32x16& p1, float& l_reg, bf16x8& pa0, bf16x8& pa1, bf16x8& pa2, bf16x8& pa3) {
;   for (int r = 0; r < 16; ++r) p1[r] = __builtin_amdgcn_exp2f(p1[r]);
;   float ps = 0; for (int r = 0; r < 16; ++r) ps += p0[r]; for (int r = 0; r < 16; ++r) ps += p1[r];
;   { auto rr = __builtin_amdgcn_permlane32_swap(__float_as_uint(ps), __float_as_uint(ps), false, false);
;     ps = __uint_as_float(rr[0]) + __uint_as_float(rr[1]); }
;   l_reg += ps;
;     ...
;   PK4(p0, 0, pa0); PK4(p0, 8, pa1); PK4(p1, 0, pa2); PK4(p1, 8, pa3);
;     ...
; }
; __device__ __forceinline__ void qkt(f32x16& p0, f32x16& p1, const bf16* Ks, const bf16x8* qr, int r32, int hi, const f32x16& negm) {
; #pragma unroll
;   for (int d0 = 0; d0 < 8; ++d0) { int cb = (d0 * 16 + hi * 8) * 2;
;     bf16x8 b0 = *reinterpret_cast<const bf16x8*>((const char*)Ks + KSWZ(r32, cb));
;     bf16x8 b1 = *reinterpret_cast<const bf16x8*>((const char*)Ks + KSWZ(32 + r32, cb));
;     if (d0 == 0) { p0 = __builtin_amdgcn_mfma_f32_32x32x16_bf16(b0, qr[0], negm, 0, 0, 0); p1 = __builtin_amdgcn_mfma_f32_32x32x16_bf16(b1, qr[0], negm, 0, 0, 0); }
;     else { p0 = __builtin_amdgcn_mfma_f32_32x32x16_bf16(b0, qr[d0], p0, 0, 0, 0); p1 = __builtin_amdgcn_mfma_f32_32x32x16_bf16(b1, qr[d0], p1, 0, 0, 0); } }
; }
; __device__ __forceinline__ int v_st(int k, int c) { const int kk = (k & ~0xC) | ((k & 4) << 1) | ((k & 8) >> 1); return ((kk >> 3) * 4 + (c >> 5)) * 512 + ((kk & 7) * 32 + (c & 31)) * 2; }
; __device__ __forceinline__ int v_rd_base(int lane) { return ((lane & 3) << 3) | (((lane >> 2) & 3) << 6) | (((lane >> 4) & 1) << 5) | (((lane >> 5) & 1) << 8); }
; template <int OFF> __device__ __forceinline__ s16x4 tr_read(int vb) {
;   s16x4 r; asm volatile("ds_read_b64_tr_b16 %0, %1 offset:%2" : "=&v"(r) : "v"(vb), "i"(OFF) : "memory"); return r;
; }
; template <int D0> __device__ __forceinline__ void pv_one(f32x16& od, int vb, bf16x8 pa0, bf16x8 pa1, bf16x8 pa2, bf16x8 pa3) {
;   const s16x4 l0 = tr_read<v_rd_off(D0, 0, 0)>(vb), h0 = tr_read<v_rd_off(D0, 0, 1)>(vb), l1 = tr_read<v_rd_off(D0, 1, 0)>(vb), h1 = tr_read<v_rd_off(D0, 1, 1)>(vb);
	s_add_u32 s98, s98, 0x8000
	s_addc_u32 s99, s99, 0
	s_add_u32 s100, s100, 0x8000
	s_addc_u32 s101, s101, 0
	s_waitcnt lgkmcnt(3)
	v_mfma_f32_16x16x32_bf16 v[114:117], v[178:181], v[146:149], v[2:5]
	v_add_f32_e32 v250, v82, v250
	v_mfma_f32_16x16x32_bf16 v[118:121], v[178:181], v[162:165], v[2:5]
	ds_read_b128 v[178:181], v235 offset:49152
	v_add_f32_e32 v250, v83, v250
	v_add_f32_e32 v250, v84, v250
	s_waitcnt lgkmcnt(3)
	v_mfma_f32_16x16x32_bf16 v[122:125], v[182:185], v[146:149], v[2:5]
	v_add_f32_e32 v250, v85, v250
	v_mfma_f32_16x16x32_bf16 v[126:129], v[182:185], v[162:165], v[2:5]
	ds_read_b128 v[182:185], v235 offset:53248
	v_add_f32_e32 v250, v90, v250
	v_add_f32_e32 v250, v91, v250
	s_add_u32 m0, s79, 32768
	s_nop 0
	global_load_lds_dwordx4 v246, s[98:99]
	s_waitcnt lgkmcnt(3)
	v_mfma_f32_16x16x32_bf16 v[130:133], v[186:189], v[146:149], v[2:5]
	v_add_f32_e32 v250, v92, v250
	v_mfma_f32_16x16x32_bf16 v[134:137], v[186:189], v[162:165], v[2:5]
	ds_read_b128 v[186:189], v235 offset:57344
	v_add_f32_e32 v250, v93, v250
	v_cvt_pk_bf16_f32 v82, v82, v83
	s_waitcnt lgkmcnt(3)
	v_mfma_f32_16x16x32_bf16 v[138:141], v[190:193], v[146:149], v[2:5]
	v_cvt_pk_bf16_f32 v83, v84, v85
	v_mfma_f32_16x16x32_bf16 v[142:145], v[190:193], v[162:165], v[2:5]
	ds_read_b128 v[190:193], v235 offset:61440
	v_cvt_pk_bf16_f32 v84, v90, v91
	v_cvt_pk_bf16_f32 v85, v92, v93
	s_waitcnt lgkmcnt(3)
	v_mfma_f32_16x16x32_bf16 v[114:117], v[178:181], v[150:153], v[114:117]
	v_add_f32_e32 v251, v86, v251
	v_mfma_f32_16x16x32_bf16 v[118:121], v[178:181], v[166:169], v[118:121]
	ds_read_b128 v[178:181], v236 offset:49152
	v_add_f32_e32 v251, v87, v251
	v_add_f32_e32 v251, v88, v251
	s_waitcnt lgkmcnt(3)
	v_mfma_f32_16x16x32_bf16 v[122:125], v[182:185], v[150:153], v[122:125]
	v_add_f32_e32 v251, v89, v251
	v_mfma_f32_16x16x32_bf16 v[126:129], v[182:185], v[166:169], v[126:129]
	ds_read_b128 v[182:185], v236 offset:53248
	v_add_f32_e32 v251, v94, v251
	v_add_f32_e32 v251, v95, v251
	s_add_u32 m0, s79, 33792
	s_nop 0
	global_load_lds_dwordx4 v247, s[98:99]
	s_waitcnt lgkmcnt(3)
	v_mfma_f32_16x16x32_bf16 v[130:133], v[186:189], v[150:153], v[130:133]
	v_add_f32_e32 v251, v96, v251
	v_mfma_f32_16x16x32_bf16 v[134:137], v[186:189], v[166:169], v[134:137]
	ds_read_b128 v[186:189], v236 offset:57344
	v_add_f32_e32 v251, v97, v251
	v_cvt_pk_bf16_f32 v86, v86, v87
	s_waitcnt lgkmcnt(3)
	v_mfma_f32_16x16x32_bf16 v[138:141], v[190:193], v[150:153], v[138:141]
	v_cvt_pk_bf16_f32 v87, v88, v89
	v_mfma_f32_16x16x32_bf16 v[142:145], v[190:193], v[166:169], v[142:145]
	ds_read_b128 v[190:193], v236 offset:61440
	v_cvt_pk_bf16_f32 v88, v94, v95
	v_cvt_pk_bf16_f32 v89, v96, v97
	s_waitcnt lgkmcnt(3)
	v_mfma_f32_16x16x32_bf16 v[114:117], v[178:181], v[154:157], v[114:117]
	v_add_f32_e32 v250, v98, v250
	v_mfma_f32_16x16x32_bf16 v[118:121], v[178:181], v[170:173], v[118:121]
	ds_read_b128 v[178:181], v237 offset:49152
	v_add_f32_e32 v250, v99, v250
	v_add_f32_e32 v250, v100, v250
	s_waitcnt lgkmcnt(3)
	v_mfma_f32_16x16x32_bf16 v[122:125], v[182:185], v[154:157], v[122:125]
	v_add_f32_e32 v250, v101, v250
	v_mfma_f32_16x16x32_bf16 v[126:129], v[182:185], v[170:173], v[126:129]
	ds_read_b128 v[182:185], v237 offset:53248
	v_add_f32_e32 v250, v106, v250
	v_add_f32_e32 v250, v107, v250
	s_add_u32 m0, s80, 16384
	s_nop 0
	global_load_lds_dwordx4 v248, s[100:101]
	s_waitcnt lgkmcnt(3)
	v_mfma_f32_16x16x32_bf16 v[130:133], v[186:189], v[154:157], v[130:133]
	v_add_f32_e32 v250, v108, v250
	ds_read_b64_tr_b16 v[202:203], v238 offset:32768
	ds_read_b64_tr_b16 v[204:205], v238 offset:36864
	v_mfma_f32_16x16x32_bf16 v[134:137], v[186:189], v[170:173], v[134:137]
	ds_read_b128 v[186:189], v237 offset:57344
	v_add_f32_e32 v250, v109, v250
	v_cvt_pk_bf16_f32 v98, v98, v99
	s_waitcnt lgkmcnt(5)
	v_mfma_f32_16x16x32_bf16 v[138:141], v[190:193], v[154:157], v[138:141]
	v_cvt_pk_bf16_f32 v99, v100, v101
	ds_read_b64_tr_b16 v[206:207], v239 offset:32768
	ds_read_b64_tr_b16 v[208:209], v239 offset:36864
	v_mfma_f32_16x16x32_bf16 v[142:145], v[190:193], v[170:173], v[142:145]
	ds_read_b128 v[190:193], v237 offset:61440
	v_cvt_pk_bf16_f32 v100, v106, v107
	v_cvt_pk_bf16_f32 v101, v108, v109
	s_waitcnt lgkmcnt(7)
	v_mfma_f32_16x16x32_bf16 v[114:117], v[178:181], v[158:161], v[114:117]
	v_add_f32_e32 v251, v102, v251
	ds_read_b64_tr_b16 v[210:211], v240 offset:32768
	ds_read_b64_tr_b16 v[212:213], v240 offset:36864
	v_mfma_f32_16x16x32_bf16 v[118:121], v[178:181], v[174:177], v[118:121]
	v_add_f32_e32 v251, v103, v251
	v_add_f32_e32 v251, v104, v251
	s_waitcnt lgkmcnt(8)
	v_mfma_f32_16x16x32_bf16 v[122:125], v[182:185], v[158:161], v[122:125]
	v_add_f32_e32 v251, v105, v251
	ds_read_b64_tr_b16 v[214:215], v241 offset:32768
	ds_read_b64_tr_b16 v[216:217], v241 offset:36864
	v_mfma_f32_16x16x32_bf16 v[126:129], v[182:185], v[174:177], v[126:129]
	v_add_f32_e32 v251, v110, v251
	v_add_f32_e32 v251, v111, v251
	s_add_u32 m0, s80, 17408
	s_nop 0
	global_load_lds_dwordx4 v249, s[100:101]
	s_waitcnt lgkmcnt(7)
	v_mfma_f32_16x16x32_bf16 v[130:133], v[186:189], v[158:161], v[130:133]
	v_add_f32_e32 v251, v112, v251
	ds_read_b64_tr_b16 v[218:219], v242 offset:32768
	ds_read_b64_tr_b16 v[220:221], v242 offset:36864
	v_mfma_f32_16x16x32_bf16 v[134:137], v[186:189], v[174:177], v[134:137]
	v_add_f32_e32 v251, v113, v251
	v_cvt_pk_bf16_f32 v102, v102, v103
	s_waitcnt lgkmcnt(6)
; __device__ __forceinline__ void partialSM(f32x16& p0, f32x16& p1, float mC) {
;   (void)mC; (void)p1;
;   for (int r = 0; r < 16; ++r) p0[r] = __builtin_amdgcn_exp2f(p0[r]);
; }
; __device__ __forceinline__ void finishSM(f32x16& p0, f32x16& p1, float& l_reg, bf16x8& pa0, bf16x8& pa1, bf16x8& pa2, bf16x8& pa3) {
;   for (int r = 0; r < 16; ++r) p1[r] = __builtin_amdgcn_exp2f(p1[r]);
;   float ps = 0; for (int r = 0; r < 16; ++r) ps += p0[r]; for (int r = 0; r < 16; ++r) ps += p1[r];
;   { auto rr = __builtin_amdgcn_permlane32_swap(__float_as_uint(ps), __float_as_uint(ps), false, false);
;     ps = __uint_as_float(rr[0]) + __uint_as_float(rr[1]); }
;   l_reg += ps;
;     ...
;   PK4(p0, 0, pa0); PK4(p0, 8, pa1); PK4(p1, 0, pa2); PK4(p1, 8, pa3);
;     ...
; }
; __device__ __forceinline__ void qkt(f32x16& p0, f32x16& p1, const bf16* Ks, const bf16x8* qr, int r32, int hi, const f32x16& negm) {
; #pragma unroll
;   for (int d0 = 0; d0 < 8; ++d0) { int cb = (d0 * 16 + hi * 8) * 2;
;     bf16x8 b0 = *reinterpret_cast<const bf16x8*>((const char*)Ks + KSWZ(r32, cb));
;     bf16x8 b1 = *reinterpret_cast<const bf16x8*>((const char*)Ks + KSWZ(32 + r32, cb));
;     if (d0 == 0) { p0 = __builtin_amdgcn_mfma_f32_32x32x16_bf16(b0, qr[0], negm, 0, 0, 0); p1 = __builtin_amdgcn_mfma_f32_32x32x16_bf16(b1, qr[0], negm, 0, 0, 0); }
;     else { p0 = __builtin_amdgcn_mfma_f32_32x32x16_bf16(b0, qr[d0], p0, 0, 0, 0); p1 = __builtin_amdgcn_mfma_f32_32x32x16_bf16(b1, qr[d0], p1, 0, 0, 0); } }
; }
; __device__ __forceinline__ int v_st(int k, int c) { const int kk = (k & ~0xC) | ((k & 4) << 1) | ((k & 8) >> 1); return ((kk >> 3) * 4 + (c >> 5)) * 512 + ((kk & 7) * 32 + (c & 31)) * 2; }
; __device__ __forceinline__ int v_rd_base(int lane) { return ((lane & 3) << 3) | (((lane >> 2) & 3) << 6) | (((lane >> 4) & 1) << 5) | (((lane >> 5) & 1) << 8); }
; template <int OFF> __device__ __forceinline__ s16x4 tr_read(int vb) {
;   s16x4 r; asm volatile("ds_read_b64_tr_b16 %0, %1 offset:%2" : "=&v"(r) : "v"(vb), "i"(OFF) : "memory"); return r;
; }
; template <int D0> __device__ __forceinline__ void pv_one(f32x16& od, int vb, bf16x8 pa0, bf16x8 pa1, bf16x8 pa2, bf16x8 pa3) {
;   const s16x4 l0 = tr_read<v_rd_off(D0, 0, 0)>(vb), h0 = tr_read<v_rd_off(D0, 0, 1)>(vb), l1 = tr_read<v_rd_off(D0, 1, 0)>(vb), h1 = tr_read<v_rd_off(D0, 1, 1)>(vb);
	v_mfma_f32_16x16x32_bf16 v[138:141], v[190:193], v[158:161], v[138:141]
	v_cvt_pk_bf16_f32 v103, v104, v105
	ds_read_b64_tr_b16 v[222:223], v243 offset:32768
	ds_read_b64_tr_b16 v[224:225], v243 offset:36864
	v_mfma_f32_16x16x32_bf16 v[142:145], v[190:193], v[174:177], v[142:145]
	v_cvt_pk_bf16_f32 v104, v110, v111
	v_cvt_pk_bf16_f32 v105, v112, v113
	v_mfma_f32_16x16x32_bf16 v[18:21], v[202:205], v[82:85], v[18:21]
	v_exp_f32_e32 v114, v114
	v_mfma_f32_16x16x32_bf16 v[22:25], v[202:205], v[86:89], v[22:25]
	ds_read_b64_tr_b16 v[202:203], v244 offset:32768
	ds_read_b64_tr_b16 v[204:205], v244 offset:36864
	v_exp_f32_e32 v115, v115
	v_mfma_f32_16x16x32_bf16 v[26:29], v[206:209], v[82:85], v[26:29]
	v_exp_f32_e32 v116, v116
	v_mfma_f32_16x16x32_bf16 v[30:33], v[206:209], v[86:89], v[30:33]
	ds_read_b64_tr_b16 v[206:207], v245 offset:32768
	ds_read_b64_tr_b16 v[208:209], v245 offset:36864
	v_exp_f32_e32 v117, v117
	s_waitcnt lgkmcnt(10)
	v_mfma_f32_16x16x32_bf16 v[34:37], v[210:213], v[82:85], v[34:37]
	v_exp_f32_e32 v118, v118
	v_mfma_f32_16x16x32_bf16 v[38:41], v[210:213], v[86:89], v[38:41]
	ds_read_b64_tr_b16 v[210:211], v238 offset:40960
	ds_read_b64_tr_b16 v[212:213], v238 offset:45056
	v_exp_f32_e32 v119, v119
	s_waitcnt lgkmcnt(10)
	v_mfma_f32_16x16x32_bf16 v[42:45], v[214:217], v[82:85], v[42:45]
	v_exp_f32_e32 v120, v120
	v_mfma_f32_16x16x32_bf16 v[46:49], v[214:217], v[86:89], v[46:49]
	ds_read_b64_tr_b16 v[214:215], v239 offset:40960
	ds_read_b64_tr_b16 v[216:217], v239 offset:45056
	v_exp_f32_e32 v121, v121
	s_waitcnt lgkmcnt(10)
	v_mfma_f32_16x16x32_bf16 v[50:53], v[218:221], v[82:85], v[50:53]
	v_exp_f32_e32 v122, v122
	v_mfma_f32_16x16x32_bf16 v[54:57], v[218:221], v[86:89], v[54:57]
	ds_read_b64_tr_b16 v[218:219], v240 offset:40960
	ds_read_b64_tr_b16 v[220:221], v240 offset:45056
	v_exp_f32_e32 v123, v123
	s_waitcnt lgkmcnt(10)
	v_mfma_f32_16x16x32_bf16 v[58:61], v[222:225], v[82:85], v[58:61]
	v_exp_f32_e32 v124, v124
	v_mfma_f32_16x16x32_bf16 v[62:65], v[222:225], v[86:89], v[62:65]
	ds_read_b64_tr_b16 v[222:223], v241 offset:40960
	ds_read_b64_tr_b16 v[224:225], v241 offset:45056
	v_exp_f32_e32 v125, v125
	s_waitcnt lgkmcnt(10)
	v_mfma_f32_16x16x32_bf16 v[66:69], v[202:205], v[82:85], v[66:69]
	v_exp_f32_e32 v126, v126
	v_mfma_f32_16x16x32_bf16 v[70:73], v[202:205], v[86:89], v[70:73]
	ds_read_b64_tr_b16 v[202:203], v242 offset:40960
	ds_read_b64_tr_b16 v[204:205], v242 offset:45056
	v_exp_f32_e32 v127, v127
	s_waitcnt lgkmcnt(10)
	v_mfma_f32_16x16x32_bf16 v[74:77], v[206:209], v[82:85], v[74:77]
	v_exp_f32_e32 v128, v128
	v_mfma_f32_16x16x32_bf16 v[78:81], v[206:209], v[86:89], v[78:81]
	ds_read_b64_tr_b16 v[206:207], v243 offset:40960
	ds_read_b64_tr_b16 v[208:209], v243 offset:45056
	v_exp_f32_e32 v129, v129
	s_waitcnt lgkmcnt(10)
	v_mfma_f32_16x16x32_bf16 v[18:21], v[210:213], v[98:101], v[18:21]
	v_exp_f32_e32 v130, v130
	v_mfma_f32_16x16x32_bf16 v[22:25], v[210:213], v[102:105], v[22:25]
	ds_read_b64_tr_b16 v[210:211], v244 offset:40960
	ds_read_b64_tr_b16 v[212:213], v244 offset:45056
	v_exp_f32_e32 v131, v131
	s_waitcnt lgkmcnt(10)
	v_mfma_f32_16x16x32_bf16 v[26:29], v[214:217], v[98:101], v[26:29]
	v_exp_f32_e32 v132, v132
	v_mfma_f32_16x16x32_bf16 v[30:33], v[214:217], v[102:105], v[30:33]
	ds_read_b64_tr_b16 v[214:215], v245 offset:40960
	ds_read_b64_tr_b16 v[216:217], v245 offset:45056
	v_exp_f32_e32 v133, v133
	s_waitcnt lgkmcnt(10)
	v_mfma_f32_16x16x32_bf16 v[34:37], v[218:221], v[98:101], v[34:37]
	v_exp_f32_e32 v134, v134
	v_mfma_f32_16x16x32_bf16 v[38:41], v[218:221], v[102:105], v[38:41]
	v_exp_f32_e32 v135, v135
	s_waitcnt lgkmcnt(8)
	v_mfma_f32_16x16x32_bf16 v[42:45], v[222:225], v[98:101], v[42:45]
	v_exp_f32_e32 v136, v136
	v_mfma_f32_16x16x32_bf16 v[46:49], v[222:225], v[102:105], v[46:49]
	v_exp_f32_e32 v137, v137
	s_waitcnt lgkmcnt(6)
	v_mfma_f32_16x16x32_bf16 v[50:53], v[202:205], v[98:101], v[50:53]
	v_exp_f32_e32 v138, v138
	ds_read_b128 v[178:181], v234 offset:0
	v_mfma_f32_16x16x32_bf16 v[54:57], v[202:205], v[102:105], v[54:57]
	v_exp_f32_e32 v139, v139
	s_waitcnt lgkmcnt(5)
	v_mfma_f32_16x16x32_bf16 v[58:61], v[206:209], v[98:101], v[58:61]
	v_exp_f32_e32 v140, v140
	ds_read_b128 v[182:185], v234 offset:4096
	v_mfma_f32_16x16x32_bf16 v[62:65], v[206:209], v[102:105], v[62:65]
	v_exp_f32_e32 v141, v141
	s_waitcnt lgkmcnt(4)
	v_mfma_f32_16x16x32_bf16 v[66:69], v[210:213], v[98:101], v[66:69]
	v_exp_f32_e32 v142, v142
	ds_read_b128 v[186:189], v234 offset:8192
	v_mfma_f32_16x16x32_bf16 v[70:73], v[210:213], v[102:105], v[70:73]
	v_exp_f32_e32 v143, v143
	s_waitcnt lgkmcnt(3)
	v_mfma_f32_16x16x32_bf16 v[74:77], v[214:217], v[98:101], v[74:77]
	v_exp_f32_e32 v144, v144
	ds_read_b128 v[190:193], v234 offset:12288
	v_mfma_f32_16x16x32_bf16 v[78:81], v[214:217], v[102:105], v[78:81]
	v_exp_f32_e32 v145, v145
	s_waitcnt vmcnt(4)
	s_barrier
; __device__ __forceinline__ void partialSM(f32x16& p0, f32x16& p1, float mC) {
;   (void)mC; (void)p1;
;   for (int r = 0; r < 16; ++r) p0[r] = __builtin_amdgcn_exp2f(p0[r]);
; }
; __device__ __forceinline__ void finishSM(f32x16& p0, f32x16& p1, float& l_reg, bf16x8& pa0, bf16x8& pa1, bf16x8& pa2, bf16x8& pa3) {
;   for (int r = 0; r < 16; ++r) p1[r] = __builtin_amdgcn_exp2f(p1[r]);
;   float ps = 0; for (int r = 0; r < 16; ++r) ps += p0[r]; for (int r = 0; r < 16; ++r) ps += p1[r];
;   { auto rr = __builtin_amdgcn_permlane32_swap(__float_as_uint(ps), __float_as_uint(ps), false, false);
;     ps = __uint_as_float(rr[0]) + __uint_as_float(rr[1]); }
;   l_reg += ps;
;     ...
;   PK4(p0, 0, pa0); PK4(p0, 8, pa1); PK4(p1, 0, pa2); PK4(p1, 8, pa3);
;     ...
; }
; __device__ __forceinline__ void qkt(f32x16& p0, f32x16& p1, const bf16* Ks, const bf16x8* qr, int r32, int hi, const f32x16& negm) {
; #pragma unroll
;   for (int d0 = 0; d0 < 8; ++d0) { int cb = (d0 * 16 + hi * 8) * 2;
;     bf16x8 b0 = *reinterpret_cast<const bf16x8*>((const char*)Ks + KSWZ(r32, cb));
;     bf16x8 b1 = *reinterpret_cast<const bf16x8*>((const char*)Ks + KSWZ(32 + r32, cb));
;     if (d0 == 0) { p0 = __builtin_amdgcn_mfma_f32_32x32x16_bf16(b0, qr[0], negm, 0, 0, 0); p1 = __builtin_amdgcn_mfma_f32_32x32x16_bf16(b1, qr[0], negm, 0, 0, 0); }
;     else { p0 = __builtin_amdgcn_mfma_f32_32x32x16_bf16(b0, qr[d0], p0, 0, 0, 0); p1 = __builtin_amdgcn_mfma_f32_32x32x16_bf16(b1, qr[d0], p1, 0, 0, 0); } }
; }
; __device__ __forceinline__ int v_st(int k, int c) { const int kk = (k & ~0xC) | ((k & 4) << 1) | ((k & 8) >> 1); return ((kk >> 3) * 4 + (c >> 5)) * 512 + ((kk & 7) * 32 + (c & 31)) * 2; }
; __device__ __forceinline__ int v_rd_base(int lane) { return ((lane & 3) << 3) | (((lane >> 2) & 3) << 6) | (((lane >> 4) & 1) << 5) | (((lane >> 5) & 1) << 8); }
; template <int OFF> __device__ __forceinline__ s16x4 tr_read(int vb) {
;   s16x4 r; asm volatile("ds_read_b64_tr_b16 %0, %1 offset:%2" : "=&v"(r) : "v"(vb), "i"(OFF) : "memory"); return r;
; }
; template <int D0> __device__ __forceinline__ void pv_one(f32x16& od, int vb, bf16x8 pa0, bf16x8 pa1, bf16x8 pa2, bf16x8 pa3) {
;   const s16x4 l0 = tr_read<v_rd_off(D0, 0, 0)>(vb), h0 = tr_read<v_rd_off(D0, 0, 1)>(vb), l1 = tr_read<v_rd_off(D0, 1, 0)>(vb), h1 = tr_read<v_rd_off(D0, 1, 1)>(vb);
	s_add_u32 s98, s98, 0x8000
	s_addc_u32 s99, s99, 0
	s_add_u32 s100, s100, 0x8000
	s_addc_u32 s101, s101, 0
	s_waitcnt lgkmcnt(3)
	v_mfma_f32_16x16x32_bf16 v[82:85], v[178:181], v[146:149], v[2:5]
	v_add_f32_e32 v250, v114, v250
	v_mfma_f32_16x16x32_bf16 v[86:89], v[178:181], v[162:165], v[2:5]
	ds_read_b128 v[178:181], v235 offset:0
	v_add_f32_e32 v250, v115, v250
	v_add_f32_e32 v250, v116, v250
	s_waitcnt lgkmcnt(3)
	v_mfma_f32_16x16x32_bf16 v[90:93], v[182:185], v[146:149], v[2:5]
	v_add_f32_e32 v250, v117, v250
	v_mfma_f32_16x16x32_bf16 v[94:97], v[182:185], v[162:165], v[2:5]
	ds_read_b128 v[182:185], v235 offset:4096
	v_add_f32_e32 v250, v122, v250
	v_add_f32_e32 v250, v123, v250
	s_add_u32 m0, s79, 49152
	s_nop 0
	global_load_lds_dwordx4 v246, s[98:99]
	s_waitcnt lgkmcnt(3)
	v_mfma_f32_16x16x32_bf16 v[98:101], v[186:189], v[146:149], v[2:5]
	v_add_f32_e32 v250, v124, v250
	v_mfma_f32_16x16x32_bf16 v[102:105], v[186:189], v[162:165], v[2:5]
	ds_read_b128 v[186:189], v235 offset:8192
	v_add_f32_e32 v250, v125, v250
	v_cvt_pk_bf16_f32 v114, v114, v115
	s_waitcnt lgkmcnt(3)
	v_mfma_f32_16x16x32_bf16 v[106:109], v[190:193], v[146:149], v[2:5]
	v_cvt_pk_bf16_f32 v115, v116, v117
	v_mfma_f32_16x16x32_bf16 v[110:113], v[190:193], v[162:165], v[2:5]
	ds_read_b128 v[190:193], v235 offset:12288
	v_cvt_pk_bf16_f32 v116, v122, v123
	v_cvt_pk_bf16_f32 v117, v124, v125
	s_waitcnt lgkmcnt(3)
	v_mfma_f32_16x16x32_bf16 v[82:85], v[178:181], v[150:153], v[82:85]
	v_add_f32_e32 v251, v118, v251
	v_mfma_f32_16x16x32_bf16 v[86:89], v[178:181], v[166:169], v[86:89]
	ds_read_b128 v[178:181], v236 offset:0
	v_add_f32_e32 v251, v119, v251
	v_add_f32_e32 v251, v120, v251
	s_waitcnt lgkmcnt(3)
	v_mfma_f32_16x16x32_bf16 v[90:93], v[182:185], v[150:153], v[90:93]
	v_add_f32_e32 v251, v121, v251
	v_mfma_f32_16x16x32_bf16 v[94:97], v[182:185], v[166:169], v[94:97]
	ds_read_b128 v[182:185], v236 offset:4096
	v_add_f32_e32 v251, v126, v251
	v_add_f32_e32 v251, v127, v251
	s_add_u32 m0, s79, 50176
	s_nop 0
	global_load_lds_dwordx4 v247, s[98:99]
	s_waitcnt lgkmcnt(3)
	v_mfma_f32_16x16x32_bf16 v[98:101], v[186:189], v[150:153], v[98:101]
	v_add_f32_e32 v251, v128, v251
	v_mfma_f32_16x16x32_bf16 v[102:105], v[186:189], v[166:169], v[102:105]
	ds_read_b128 v[186:189], v236 offset:8192
	v_add_f32_e32 v251, v129, v251
	v_cvt_pk_bf16_f32 v118, v118, v119
	s_waitcnt lgkmcnt(3)
	v_mfma_f32_16x16x32_bf16 v[106:109], v[190:193], v[150:153], v[106:109]
	v_cvt_pk_bf16_f32 v119, v120, v121
	v_mfma_f32_16x16x32_bf16 v[110:113], v[190:193], v[166:169], v[110:113]
	ds_read_b128 v[190:193], v236 offset:12288
	v_cvt_pk_bf16_f32 v120, v126, v127
	v_cvt_pk_bf16_f32 v121, v128, v129
	s_waitcnt lgkmcnt(3)
	v_mfma_f32_16x16x32_bf16 v[82:85], v[178:181], v[154:157], v[82:85]
	v_add_f32_e32 v250, v130, v250
	v_mfma_f32_16x16x32_bf16 v[86:89], v[178:181], v[170:173], v[86:89]
	ds_read_b128 v[178:181], v237 offset:0
	v_add_f32_e32 v250, v131, v250
	v_add_f32_e32 v250, v132, v250
	s_waitcnt lgkmcnt(3)
	v_mfma_f32_16x16x32_bf16 v[90:93], v[182:185], v[154:157], v[90:93]
	v_add_f32_e32 v250, v133, v250
	v_mfma_f32_16x16x32_bf16 v[94:97], v[182:185], v[170:173], v[94:97]
	ds_read_b128 v[182:185], v237 offset:4096
	v_add_f32_e32 v250, v138, v250
	v_add_f32_e32 v250, v139, v250
	s_add_u32 m0, s80, 32768
	s_nop 0
	global_load_lds_dwordx4 v248, s[100:101]
	s_waitcnt lgkmcnt(3)
	v_mfma_f32_16x16x32_bf16 v[98:101], v[186:189], v[154:157], v[98:101]
	v_add_f32_e32 v250, v140, v250
	ds_read_b64_tr_b16 v[202:203], v238 offset:49152
	ds_read_b64_tr_b16 v[204:205], v238 offset:53248
	v_mfma_f32_16x16x32_bf16 v[102:105], v[186:189], v[170:173], v[102:105]
	ds_read_b128 v[186:189], v237 offset:8192
	v_add_f32_e32 v250, v141, v250
	v_cvt_pk_bf16_f32 v130, v130, v131
	s_waitcnt lgkmcnt(5)
	v_mfma_f32_16x16x32_bf16 v[106:109], v[190:193], v[154:157], v[106:109]
	v_cvt_pk_bf16_f32 v131, v132, v133
	ds_read_b64_tr_b16 v[206:207], v239 offset:49152
	ds_read_b64_tr_b16 v[208:209], v239 offset:53248
	v_mfma_f32_16x16x32_bf16 v[110:113], v[190:193], v[170:173], v[110:113]
	ds_read_b128 v[190:193], v237 offset:12288
	v_cvt_pk_bf16_f32 v132, v138, v139
	v_cvt_pk_bf16_f32 v133, v140, v141
	s_waitcnt lgkmcnt(7)
	v_mfma_f32_16x16x32_bf16 v[82:85], v[178:181], v[158:161], v[82:85]
	v_add_f32_e32 v251, v134, v251
	ds_read_b64_tr_b16 v[210:211], v240 offset:49152
	ds_read_b64_tr_b16 v[212:213], v240 offset:53248
	v_mfma_f32_16x16x32_bf16 v[86:89], v[178:181], v[174:177], v[86:89]
	v_add_f32_e32 v251, v135, v251
	v_add_f32_e32 v251, v136, v251
	s_waitcnt lgkmcnt(8)
	v_mfma_f32_16x16x32_bf16 v[90:93], v[182:185], v[158:161], v[90:93]
	v_add_f32_e32 v251, v137, v251
	ds_read_b64_tr_b16 v[214:215], v241 offset:49152
	ds_read_b64_tr_b16 v[216:217], v241 offset:53248
	v_mfma_f32_16x16x32_bf16 v[94:97], v[182:185], v[174:177], v[94:97]
	v_add_f32_e32 v251, v142, v251
	v_add_f32_e32 v251, v143, v251
	s_add_u32 m0, s80, 33792
	s_nop 0
	global_load_lds_dwordx4 v249, s[100:101]
	s_waitcnt lgkmcnt(7)
	v_mfma_f32_16x16x32_bf16 v[98:101], v[186:189], v[158:161], v[98:101]
	v_add_f32_e32 v251, v144, v251
	ds_read_b64_tr_b16 v[218:219], v242 offset:49152
	ds_read_b64_tr_b16 v[220:221], v242 offset:53248
	v_mfma_f32_16x16x32_bf16 v[102:105], v[186:189], v[174:177], v[102:105]
	v_add_f32_e32 v251, v145, v251
	v_cvt_pk_bf16_f32 v134, v134, v135
	s_waitcnt lgkmcnt(6)
; __device__ __forceinline__ void partialSM(f32x16& p0, f32x16& p1, float mC) {
;   (void)mC; (void)p1;
;   for (int r = 0; r < 16; ++r) p0[r] = __builtin_amdgcn_exp2f(p0[r]);
; }
; __device__ __forceinline__ void finishSM(f32x16& p0, f32x16& p1, float& l_reg, bf16x8& pa0, bf16x8& pa1, bf16x8& pa2, bf16x8& pa3) {
;   for (int r = 0; r < 16; ++r) p1[r] = __builtin_amdgcn_exp2f(p1[r]);
;   float ps = 0; for (int r = 0; r < 16; ++r) ps += p0[r]; for (int r = 0; r < 16; ++r) ps += p1[r];
;   { auto rr = __builtin_amdgcn_permlane32_swap(__float_as_uint(ps), __float_as_uint(ps), false, false);
;     ps = __uint_as_float(rr[0]) + __uint_as_float(rr[1]); }
;   l_reg += ps;
;     ...
;   PK4(p0, 0, pa0); PK4(p0, 8, pa1); PK4(p1, 0, pa2); PK4(p1, 8, pa3);
;     ...
; }
; __device__ __forceinline__ void qkt(f32x16& p0, f32x16& p1, const bf16* Ks, const bf16x8* qr, int r32, int hi, const f32x16& negm) {
; #pragma unroll
;   for (int d0 = 0; d0 < 8; ++d0) { int cb = (d0 * 16 + hi * 8) * 2;
;     bf16x8 b0 = *reinterpret_cast<const bf16x8*>((const char*)Ks + KSWZ(r32, cb));
;     bf16x8 b1 = *reinterpret_cast<const bf16x8*>((const char*)Ks + KSWZ(32 + r32, cb));
;     if (d0 == 0) { p0 = __builtin_amdgcn_mfma_f32_32x32x16_bf16(b0, qr[0], negm, 0, 0, 0); p1 = __builtin_amdgcn_mfma_f32_32x32x16_bf16(b1, qr[0], negm, 0, 0, 0); }
;     else { p0 = __builtin_amdgcn_mfma_f32_32x32x16_bf16(b0, qr[d0], p0, 0, 0, 0); p1 = __builtin_amdgcn_mfma_f32_32x32x16_bf16(b1, qr[d0], p1, 0, 0, 0); } }
; }
; __device__ __forceinline__ int v_st(int k, int c) { const int kk = (k & ~0xC) | ((k & 4) << 1) | ((k & 8) >> 1); return ((kk >> 3) * 4 + (c >> 5)) * 512 + ((kk & 7) * 32 + (c & 31)) * 2; }
; __device__ __forceinline__ int v_rd_base(int lane) { return ((lane & 3) << 3) | (((lane >> 2) & 3) << 6) | (((lane >> 4) & 1) << 5) | (((lane >> 5) & 1) << 8); }
; template <int OFF> __device__ __forceinline__ s16x4 tr_read(int vb) {
;   s16x4 r; asm volatile("ds_read_b64_tr_b16 %0, %1 offset:%2" : "=&v"(r) : "v"(vb), "i"(OFF) : "memory"); return r;
; }
; template <int D0> __device__ __forceinline__ void pv_one(f32x16& od, int vb, bf16x8 pa0, bf16x8 pa1, bf16x8 pa2, bf16x8 pa3) {
;   const s16x4 l0 = tr_read<v_rd_off(D0, 0, 0)>(vb), h0 = tr_read<v_rd_off(D0, 0, 1)>(vb), l1 = tr_read<v_rd_off(D0, 1, 0)>(vb), h1 = tr_read<v_rd_off(D0, 1, 1)>(vb);
	v_mfma_f32_16x16x32_bf16 v[106:109], v[190:193], v[158:161], v[106:109]
	v_cvt_pk_bf16_f32 v135, v136, v137
	ds_read_b64_tr_b16 v[222:223], v243 offset:49152
	ds_read_b64_tr_b16 v[224:225], v243 offset:53248
	v_mfma_f32_16x16x32_bf16 v[110:113], v[190:193], v[174:177], v[110:113]
	v_cvt_pk_bf16_f32 v136, v142, v143
	v_cvt_pk_bf16_f32 v137, v144, v145
	v_mfma_f32_16x16x32_bf16 v[18:21], v[202:205], v[114:117], v[18:21]
	v_exp_f32_e32 v82, v82
	v_mfma_f32_16x16x32_bf16 v[22:25], v[202:205], v[118:121], v[22:25]
	ds_read_b64_tr_b16 v[202:203], v244 offset:49152
	ds_read_b64_tr_b16 v[204:205], v244 offset:53248
	v_exp_f32_e32 v83, v83
	v_mfma_f32_16x16x32_bf16 v[26:29], v[206:209], v[114:117], v[26:29]
	v_exp_f32_e32 v84, v84
	v_mfma_f32_16x16x32_bf16 v[30:33], v[206:209], v[118:121], v[30:33]
	ds_read_b64_tr_b16 v[206:207], v245 offset:49152
	ds_read_b64_tr_b16 v[208:209], v245 offset:53248
	v_exp_f32_e32 v85, v85
	s_waitcnt lgkmcnt(10)
	v_mfma_f32_16x16x32_bf16 v[34:37], v[210:213], v[114:117], v[34:37]
	v_exp_f32_e32 v86, v86
	v_mfma_f32_16x16x32_bf16 v[38:41], v[210:213], v[118:121], v[38:41]
	ds_read_b64_tr_b16 v[210:211], v238 offset:57344
	ds_read_b64_tr_b16 v[212:213], v238 offset:61440
	v_exp_f32_e32 v87, v87
	s_waitcnt lgkmcnt(10)
	v_mfma_f32_16x16x32_bf16 v[42:45], v[214:217], v[114:117], v[42:45]
	v_exp_f32_e32 v88, v88
	v_mfma_f32_16x16x32_bf16 v[46:49], v[214:217], v[118:121], v[46:49]
	ds_read_b64_tr_b16 v[214:215], v239 offset:57344
	ds_read_b64_tr_b16 v[216:217], v239 offset:61440
	v_exp_f32_e32 v89, v89
	s_waitcnt lgkmcnt(10)
	v_mfma_f32_16x16x32_bf16 v[50:53], v[218:221], v[114:117], v[50:53]
	v_exp_f32_e32 v90, v90
	v_mfma_f32_16x16x32_bf16 v[54:57], v[218:221], v[118:121], v[54:57]
	ds_read_b64_tr_b16 v[218:219], v240 offset:57344
	ds_read_b64_tr_b16 v[220:221], v240 offset:61440
	v_exp_f32_e32 v91, v91
	s_waitcnt lgkmcnt(10)
	v_mfma_f32_16x16x32_bf16 v[58:61], v[222:225], v[114:117], v[58:61]
	v_exp_f32_e32 v92, v92
	v_mfma_f32_16x16x32_bf16 v[62:65], v[222:225], v[118:121], v[62:65]
	ds_read_b64_tr_b16 v[222:223], v241 offset:57344
	ds_read_b64_tr_b16 v[224:225], v241 offset:61440
	v_exp_f32_e32 v93, v93
	s_waitcnt lgkmcnt(10)
	v_mfma_f32_16x16x32_bf16 v[66:69], v[202:205], v[114:117], v[66:69]
	v_exp_f32_e32 v94, v94
	v_mfma_f32_16x16x32_bf16 v[70:73], v[202:205], v[118:121], v[70:73]
	ds_read_b64_tr_b16 v[202:203], v242 offset:57344
	ds_read_b64_tr_b16 v[204:205], v242 offset:61440
	v_exp_f32_e32 v95, v95
	s_waitcnt lgkmcnt(10)
	v_mfma_f32_16x16x32_bf16 v[74:77], v[206:209], v[114:117], v[74:77]
	v_exp_f32_e32 v96, v96
	v_mfma_f32_16x16x32_bf16 v[78:81], v[206:209], v[118:121], v[78:81]
	ds_read_b64_tr_b16 v[206:207], v243 offset:57344
	ds_read_b64_tr_b16 v[208:209], v243 offset:61440
	v_exp_f32_e32 v97, v97
	s_waitcnt lgkmcnt(10)
	v_mfma_f32_16x16x32_bf16 v[18:21], v[210:213], v[130:133], v[18:21]
	v_exp_f32_e32 v98, v98
	v_mfma_f32_16x16x32_bf16 v[22:25], v[210:213], v[134:137], v[22:25]
	ds_read_b64_tr_b16 v[210:211], v244 offset:57344
	ds_read_b64_tr_b16 v[212:213], v244 offset:61440
	v_exp_f32_e32 v99, v99
	s_waitcnt lgkmcnt(10)
	v_mfma_f32_16x16x32_bf16 v[26:29], v[214:217], v[130:133], v[26:29]
	v_exp_f32_e32 v100, v100
	v_mfma_f32_16x16x32_bf16 v[30:33], v[214:217], v[134:137], v[30:33]
	ds_read_b64_tr_b16 v[214:215], v245 offset:57344
	ds_read_b64_tr_b16 v[216:217], v245 offset:61440
	v_exp_f32_e32 v101, v101
	s_waitcnt lgkmcnt(10)
	v_mfma_f32_16x16x32_bf16 v[34:37], v[218:221], v[130:133], v[34:37]
	v_exp_f32_e32 v102, v102
	v_mfma_f32_16x16x32_bf16 v[38:41], v[218:221], v[134:137], v[38:41]
	v_exp_f32_e32 v103, v103
	s_waitcnt lgkmcnt(8)
	v_mfma_f32_16x16x32_bf16 v[42:45], v[222:225], v[130:133], v[42:45]
	v_exp_f32_e32 v104, v104
	v_mfma_f32_16x16x32_bf16 v[46:49], v[222:225], v[134:137], v[46:49]
	v_exp_f32_e32 v105, v105
	s_waitcnt lgkmcnt(6)
	v_mfma_f32_16x16x32_bf16 v[50:53], v[202:205], v[130:133], v[50:53]
	v_exp_f32_e32 v106, v106
	ds_read_b128 v[178:181], v234 offset:16384
	v_mfma_f32_16x16x32_bf16 v[54:57], v[202:205], v[134:137], v[54:57]
	v_exp_f32_e32 v107, v107
	s_waitcnt lgkmcnt(5)
	v_mfma_f32_16x16x32_bf16 v[58:61], v[206:209], v[130:133], v[58:61]
	v_exp_f32_e32 v108, v108
	ds_read_b128 v[182:185], v234 offset:20480
	v_mfma_f32_16x16x32_bf16 v[62:65], v[206:209], v[134:137], v[62:65]
	v_exp_f32_e32 v109, v109
	s_waitcnt lgkmcnt(4)
	v_mfma_f32_16x16x32_bf16 v[66:69], v[210:213], v[130:133], v[66:69]
	v_exp_f32_e32 v110, v110
	ds_read_b128 v[186:189], v234 offset:24576
	v_mfma_f32_16x16x32_bf16 v[70:73], v[210:213], v[134:137], v[70:73]
	v_exp_f32_e32 v111, v111
	s_waitcnt lgkmcnt(3)
	v_mfma_f32_16x16x32_bf16 v[74:77], v[214:217], v[130:133], v[74:77]
	v_exp_f32_e32 v112, v112
	ds_read_b128 v[190:193], v234 offset:28672
	v_mfma_f32_16x16x32_bf16 v[78:81], v[214:217], v[134:137], v[78:81]
	v_exp_f32_e32 v113, v113
	s_waitcnt vmcnt(4)
	s_add_i32 s15, s15, 1
	s_cmp_lt_u32 s15, 32
	s_cbranch_scc1 .Lattn_loop
	s_barrier
; __device__ __forceinline__ void partialSM(f32x16& p0, f32x16& p1, float mC) {
;   (void)mC; (void)p1;
;   for (int r = 0; r < 16; ++r) p0[r] = __builtin_amdgcn_exp2f(p0[r]);
; }
; __device__ __forceinline__ void finishSM(f32x16& p0, f32x16& p1, float& l_reg, bf16x8& pa0, bf16x8& pa1, bf16x8& pa2, bf16x8& pa3) {
;   for (int r = 0; r < 16; ++r) p1[r] = __builtin_amdgcn_exp2f(p1[r]);
;   float ps = 0; for (int r = 0; r < 16; ++r) ps += p0[r]; for (int r = 0; r < 16; ++r) ps += p1[r];
;   { auto rr = __builtin_amdgcn_permlane32_swap(__float_as_uint(ps), __float_as_uint(ps), false, false);
;     ps = __uint_as_float(rr[0]) + __uint_as_float(rr[1]); }
;   l_reg += ps;
;     ...
;   PK4(p0, 0, pa0); PK4(p0, 8, pa1); PK4(p1, 0, pa2); PK4(p1, 8, pa3);
;     ...
; }
; __device__ __forceinline__ void qkt(f32x16& p0, f32x16& p1, const bf16* Ks, const bf16x8* qr, int r32, int hi, const f32x16& negm) {
; #pragma unroll
;   for (int d0 = 0; d0 < 8; ++d0) { int cb = (d0 * 16 + hi * 8) * 2;
;     bf16x8 b0 = *reinterpret_cast<const bf16x8*>((const char*)Ks + KSWZ(r32, cb));
;     bf16x8 b1 = *reinterpret_cast<const bf16x8*>((const char*)Ks + KSWZ(32 + r32, cb));
;     if (d0 == 0) { p0 = __builtin_amdgcn_mfma_f32_32x32x16_bf16(b0, qr[0], negm, 0, 0, 0); p1 = __builtin_amdgcn_mfma_f32_32x32x16_bf16(b1, qr[0], negm, 0, 0, 0); }
;     else { p0 = __builtin_amdgcn_mfma_f32_32x32x16_bf16(b0, qr[d0], p0, 0, 0, 0); p1 = __builtin_amdgcn_mfma_f32_32x32x16_bf16(b1, qr[d0], p1, 0, 0, 0); } }
; }
; __device__ __forceinline__ int v_st(int k, int c) { const int kk = (k & ~0xC) | ((k & 4) << 1) | ((k & 8) >> 1); return ((kk >> 3) * 4 + (c >> 5)) * 512 + ((kk & 7) * 32 + (c & 31)) * 2; }
; __device__ __forceinline__ int v_rd_base(int lane) { return ((lane & 3) << 3) | (((lane >> 2) & 3) << 6) | (((lane >> 4) & 1) << 5) | (((lane >> 5) & 1) << 8); }
; template <int OFF> __device__ __forceinline__ s16x4 tr_read(int vb) {
;   s16x4 r; asm volatile("ds_read_b64_tr_b16 %0, %1 offset:%2" : "=&v"(r) : "v"(vb), "i"(OFF) : "memory"); return r;
; }
; template <typename TQ> ...
;     ...
;   SBAR(); qkt(pB0, pB1, (bf16*)((char*)K_lds + SHM_K), qr, r32, hi, negm);
;   finishSM(pA0, pA1, l_reg, pa0, pa1, pa2, pa3); SBAR();
;   pv_d0(o, vb0, pa0, pa1, pa2, pa3); partialSM(pB0, pB1, mC);
;   __syncthreads();
;   finishSM(pB0, pB1, l_reg, pa0, pa1, pa2, pa3); SBAR();
;   pv_d0(o, vb0 + (int)SHM_V, pa0, pa1, pa2, pa3);
	s_add_u32 s98, s98, 0x8000
	s_addc_u32 s99, s99, 0
	s_add_u32 s100, s100, 0x8000
	s_addc_u32 s101, s101, 0
	s_waitcnt lgkmcnt(3)
	v_mfma_f32_16x16x32_bf16 v[114:117], v[178:181], v[146:149], v[2:5]
	v_add_f32_e32 v250, v82, v250
	v_mfma_f32_16x16x32_bf16 v[118:121], v[178:181], v[162:165], v[2:5]
	ds_read_b128 v[178:181], v235 offset:16384
	v_add_f32_e32 v250, v83, v250
	v_add_f32_e32 v250, v84, v250
	s_waitcnt lgkmcnt(3)
	v_mfma_f32_16x16x32_bf16 v[122:125], v[182:185], v[146:149], v[2:5]
	v_add_f32_e32 v250, v85, v250
	v_mfma_f32_16x16x32_bf16 v[126:129], v[182:185], v[162:165], v[2:5]
	ds_read_b128 v[182:185], v235 offset:20480
	v_add_f32_e32 v250, v90, v250
	v_add_f32_e32 v250, v91, v250
	s_add_u32 m0, s80, 49152
	s_nop 0
	global_load_lds_dwordx4 v248, s[100:101]
	s_waitcnt lgkmcnt(3)
	v_mfma_f32_16x16x32_bf16 v[130:133], v[186:189], v[146:149], v[2:5]
	v_add_f32_e32 v250, v92, v250
	v_mfma_f32_16x16x32_bf16 v[134:137], v[186:189], v[162:165], v[2:5]
	ds_read_b128 v[186:189], v235 offset:24576
	v_add_f32_e32 v250, v93, v250
	v_cvt_pk_bf16_f32 v82, v82, v83
	s_waitcnt lgkmcnt(3)
	v_mfma_f32_16x16x32_bf16 v[138:141], v[190:193], v[146:149], v[2:5]
	v_cvt_pk_bf16_f32 v83, v84, v85
	v_mfma_f32_16x16x32_bf16 v[142:145], v[190:193], v[162:165], v[2:5]
	ds_read_b128 v[190:193], v235 offset:28672
	v_cvt_pk_bf16_f32 v84, v90, v91
	v_cvt_pk_bf16_f32 v85, v92, v93
	s_waitcnt lgkmcnt(3)
	v_mfma_f32_16x16x32_bf16 v[114:117], v[178:181], v[150:153], v[114:117]
	v_add_f32_e32 v251, v86, v251
	v_mfma_f32_16x16x32_bf16 v[118:121], v[178:181], v[166:169], v[118:121]
	ds_read_b128 v[178:181], v236 offset:16384
	v_add_f32_e32 v251, v87, v251
	v_add_f32_e32 v251, v88, v251
	s_waitcnt lgkmcnt(3)
	v_mfma_f32_16x16x32_bf16 v[122:125], v[182:185], v[150:153], v[122:125]
	v_add_f32_e32 v251, v89, v251
	v_mfma_f32_16x16x32_bf16 v[126:129], v[182:185], v[166:169], v[126:129]
	ds_read_b128 v[182:185], v236 offset:20480
	v_add_f32_e32 v251, v94, v251
	v_add_f32_e32 v251, v95, v251
	s_add_u32 m0, s80, 50176
	s_nop 0
	global_load_lds_dwordx4 v249, s[100:101]
	s_waitcnt lgkmcnt(3)
	v_mfma_f32_16x16x32_bf16 v[130:133], v[186:189], v[150:153], v[130:133]
	v_add_f32_e32 v251, v96, v251
	v_mfma_f32_16x16x32_bf16 v[134:137], v[186:189], v[166:169], v[134:137]
	ds_read_b128 v[186:189], v236 offset:24576
	v_add_f32_e32 v251, v97, v251
	v_cvt_pk_bf16_f32 v86, v86, v87
	s_waitcnt lgkmcnt(3)
	v_mfma_f32_16x16x32_bf16 v[138:141], v[190:193], v[150:153], v[138:141]
	v_cvt_pk_bf16_f32 v87, v88, v89
	v_mfma_f32_16x16x32_bf16 v[142:145], v[190:193], v[166:169], v[142:145]
	ds_read_b128 v[190:193], v236 offset:28672
	v_cvt_pk_bf16_f32 v88, v94, v95
	v_cvt_pk_bf16_f32 v89, v96, v97
	s_waitcnt lgkmcnt(3)
	v_mfma_f32_16x16x32_bf16 v[114:117], v[178:181], v[154:157], v[114:117]
	v_add_f32_e32 v250, v98, v250
	v_mfma_f32_16x16x32_bf16 v[118:121], v[178:181], v[170:173], v[118:121]
	ds_read_b128 v[178:181], v237 offset:16384
	v_add_f32_e32 v250, v99, v250
	v_add_f32_e32 v250, v100, v250
	s_waitcnt lgkmcnt(3)
	v_mfma_f32_16x16x32_bf16 v[122:125], v[182:185], v[154:157], v[122:125]
	v_add_f32_e32 v250, v101, v250
	v_mfma_f32_16x16x32_bf16 v[126:129], v[182:185], v[170:173], v[126:129]
	ds_read_b128 v[182:185], v237 offset:20480
	v_add_f32_e32 v250, v106, v250
	v_add_f32_e32 v250, v107, v250
	s_waitcnt lgkmcnt(3)
	v_mfma_f32_16x16x32_bf16 v[130:133], v[186:189], v[154:157], v[130:133]
	v_add_f32_e32 v250, v108, v250
	ds_read_b64_tr_b16 v[202:203], v238 offset:0
	ds_read_b64_tr_b16 v[204:205], v238 offset:4096
	v_mfma_f32_16x16x32_bf16 v[134:137], v[186:189], v[170:173], v[134:137]
	ds_read_b128 v[186:189], v237 offset:24576
	v_add_f32_e32 v250, v109, v250
	v_cvt_pk_bf16_f32 v98, v98, v99
	s_waitcnt lgkmcnt(5)
	v_mfma_f32_16x16x32_bf16 v[138:141], v[190:193], v[154:157], v[138:141]
	v_cvt_pk_bf16_f32 v99, v100, v101
	ds_read_b64_tr_b16 v[206:207], v239 offset:0
	ds_read_b64_tr_b16 v[208:209], v239 offset:4096
	v_mfma_f32_16x16x32_bf16 v[142:145], v[190:193], v[170:173], v[142:145]
	ds_read_b128 v[190:193], v237 offset:28672
	v_cvt_pk_bf16_f32 v100, v106, v107
	v_cvt_pk_bf16_f32 v101, v108, v109
	s_waitcnt lgkmcnt(7)
	v_mfma_f32_16x16x32_bf16 v[114:117], v[178:181], v[158:161], v[114:117]
	v_add_f32_e32 v251, v102, v251
	ds_read_b64_tr_b16 v[210:211], v240 offset:0
	ds_read_b64_tr_b16 v[212:213], v240 offset:4096
	v_mfma_f32_16x16x32_bf16 v[118:121], v[178:181], v[174:177], v[118:121]
	v_add_f32_e32 v251, v103, v251
	v_add_f32_e32 v251, v104, v251
	s_waitcnt lgkmcnt(8)
	v_mfma_f32_16x16x32_bf16 v[122:125], v[182:185], v[158:161], v[122:125]
	v_add_f32_e32 v251, v105, v251
	ds_read_b64_tr_b16 v[214:215], v241 offset:0
	ds_read_b64_tr_b16 v[216:217], v241 offset:4096
	v_mfma_f32_16x16x32_bf16 v[126:129], v[182:185], v[174:177], v[126:129]
	v_add_f32_e32 v251, v110, v251
	v_add_f32_e32 v251, v111, v251
	s_waitcnt lgkmcnt(7)
	v_mfma_f32_16x16x32_bf16 v[130:133], v[186:189], v[158:161], v[130:133]
	v_add_f32_e32 v251, v112, v251
	ds_read_b64_tr_b16 v[218:219], v242 offset:0
	ds_read_b64_tr_b16 v[220:221], v242 offset:4096
	v_mfma_f32_16x16x32_bf16 v[134:137], v[186:189], v[174:177], v[134:137]
	v_add_f32_e32 v251, v113, v251
	v_cvt_pk_bf16_f32 v102, v102, v103
	s_waitcnt lgkmcnt(6)
; __device__ __forceinline__ void partialSM(f32x16& p0, f32x16& p1, float mC) {
;   (void)mC; (void)p1;
;   for (int r = 0; r < 16; ++r) p0[r] = __builtin_amdgcn_exp2f(p0[r]);
; }
; __device__ __forceinline__ void finishSM(f32x16& p0, f32x16& p1, float& l_reg, bf16x8& pa0, bf16x8& pa1, bf16x8& pa2, bf16x8& pa3) {
;   for (int r = 0; r < 16; ++r) p1[r] = __builtin_amdgcn_exp2f(p1[r]);
;   float ps = 0; for (int r = 0; r < 16; ++r) ps += p0[r]; for (int r = 0; r < 16; ++r) ps += p1[r];
;   { auto rr = __builtin_amdgcn_permlane32_swap(__float_as_uint(ps), __float_as_uint(ps), false, false);
;     ps = __uint_as_float(rr[0]) + __uint_as_float(rr[1]); }
;   l_reg += ps;
;     ...
;   PK4(p0, 0, pa0); PK4(p0, 8, pa1); PK4(p1, 0, pa2); PK4(p1, 8, pa3);
;     ...
; }
; __device__ __forceinline__ void qkt(f32x16& p0, f32x16& p1, const bf16* Ks, const bf16x8* qr, int r32, int hi, const f32x16& negm) {
; #pragma unroll
;   for (int d0 = 0; d0 < 8; ++d0) { int cb = (d0 * 16 + hi * 8) * 2;
;     bf16x8 b0 = *reinterpret_cast<const bf16x8*>((const char*)Ks + KSWZ(r32, cb));
;     bf16x8 b1 = *reinterpret_cast<const bf16x8*>((const char*)Ks + KSWZ(32 + r32, cb));
;     if (d0 == 0) { p0 = __builtin_amdgcn_mfma_f32_32x32x16_bf16(b0, qr[0], negm, 0, 0, 0); p1 = __builtin_amdgcn_mfma_f32_32x32x16_bf16(b1, qr[0], negm, 0, 0, 0); }
;     else { p0 = __builtin_amdgcn_mfma_f32_32x32x16_bf16(b0, qr[d0], p0, 0, 0, 0); p1 = __builtin_amdgcn_mfma_f32_32x32x16_bf16(b1, qr[d0], p1, 0, 0, 0); } }
; }
; __device__ __forceinline__ int v_st(int k, int c) { const int kk = (k & ~0xC) | ((k & 4) << 1) | ((k & 8) >> 1); return ((kk >> 3) * 4 + (c >> 5)) * 512 + ((kk & 7) * 32 + (c & 31)) * 2; }
; __device__ __forceinline__ int v_rd_base(int lane) { return ((lane & 3) << 3) | (((lane >> 2) & 3) << 6) | (((lane >> 4) & 1) << 5) | (((lane >> 5) & 1) << 8); }
; template <int OFF> __device__ __forceinline__ s16x4 tr_read(int vb) {
;   s16x4 r; asm volatile("ds_read_b64_tr_b16 %0, %1 offset:%2" : "=&v"(r) : "v"(vb), "i"(OFF) : "memory"); return r;
; }
; template <typename TQ> ...
;     ...
;   SBAR(); qkt(pB0, pB1, (bf16*)((char*)K_lds + SHM_K), qr, r32, hi, negm);
;   finishSM(pA0, pA1, l_reg, pa0, pa1, pa2, pa3); SBAR();
;   pv_d0(o, vb0, pa0, pa1, pa2, pa3); partialSM(pB0, pB1, mC);
;   __syncthreads();
;   finishSM(pB0, pB1, l_reg, pa0, pa1, pa2, pa3); SBAR();
;   pv_d0(o, vb0 + (int)SHM_V, pa0, pa1, pa2, pa3);
	v_mfma_f32_16x16x32_bf16 v[138:141], v[190:193], v[158:161], v[138:141]
	v_cvt_pk_bf16_f32 v103, v104, v105
	ds_read_b64_tr_b16 v[222:223], v243 offset:0
	ds_read_b64_tr_b16 v[224:225], v243 offset:4096
	v_mfma_f32_16x16x32_bf16 v[142:145], v[190:193], v[174:177], v[142:145]
	v_cvt_pk_bf16_f32 v104, v110, v111
	v_cvt_pk_bf16_f32 v105, v112, v113
	v_mfma_f32_16x16x32_bf16 v[18:21], v[202:205], v[82:85], v[18:21]
	v_exp_f32_e32 v114, v114
	v_mfma_f32_16x16x32_bf16 v[22:25], v[202:205], v[86:89], v[22:25]
	ds_read_b64_tr_b16 v[202:203], v244 offset:0
	ds_read_b64_tr_b16 v[204:205], v244 offset:4096
	v_exp_f32_e32 v115, v115
	v_mfma_f32_16x16x32_bf16 v[26:29], v[206:209], v[82:85], v[26:29]
	v_exp_f32_e32 v116, v116
	v_mfma_f32_16x16x32_bf16 v[30:33], v[206:209], v[86:89], v[30:33]
	ds_read_b64_tr_b16 v[206:207], v245 offset:0
	ds_read_b64_tr_b16 v[208:209], v245 offset:4096
	v_exp_f32_e32 v117, v117
	s_waitcnt lgkmcnt(10)
	v_mfma_f32_16x16x32_bf16 v[34:37], v[210:213], v[82:85], v[34:37]
	v_exp_f32_e32 v118, v118
	v_mfma_f32_16x16x32_bf16 v[38:41], v[210:213], v[86:89], v[38:41]
	ds_read_b64_tr_b16 v[210:211], v238 offset:8192
	ds_read_b64_tr_b16 v[212:213], v238 offset:12288
	v_exp_f32_e32 v119, v119
	s_waitcnt lgkmcnt(10)
	v_mfma_f32_16x16x32_bf16 v[42:45], v[214:217], v[82:85], v[42:45]
	v_exp_f32_e32 v120, v120
	v_mfma_f32_16x16x32_bf16 v[46:49], v[214:217], v[86:89], v[46:49]
	ds_read_b64_tr_b16 v[214:215], v239 offset:8192
	ds_read_b64_tr_b16 v[216:217], v239 offset:12288
	v_exp_f32_e32 v121, v121
	s_waitcnt lgkmcnt(10)
	v_mfma_f32_16x16x32_bf16 v[50:53], v[218:221], v[82:85], v[50:53]
	v_exp_f32_e32 v122, v122
	v_mfma_f32_16x16x32_bf16 v[54:57], v[218:221], v[86:89], v[54:57]
	ds_read_b64_tr_b16 v[218:219], v240 offset:8192
	ds_read_b64_tr_b16 v[220:221], v240 offset:12288
	v_exp_f32_e32 v123, v123
	s_waitcnt lgkmcnt(10)
	v_mfma_f32_16x16x32_bf16 v[58:61], v[222:225], v[82:85], v[58:61]
	v_exp_f32_e32 v124, v124
	v_mfma_f32_16x16x32_bf16 v[62:65], v[222:225], v[86:89], v[62:65]
	ds_read_b64_tr_b16 v[222:223], v241 offset:8192
	ds_read_b64_tr_b16 v[224:225], v241 offset:12288
	v_exp_f32_e32 v125, v125
	s_waitcnt lgkmcnt(10)
	v_mfma_f32_16x16x32_bf16 v[66:69], v[202:205], v[82:85], v[66:69]
	v_exp_f32_e32 v126, v126
	v_mfma_f32_16x16x32_bf16 v[70:73], v[202:205], v[86:89], v[70:73]
	ds_read_b64_tr_b16 v[202:203], v242 offset:8192
	ds_read_b64_tr_b16 v[204:205], v242 offset:12288
	v_exp_f32_e32 v127, v127
	s_waitcnt lgkmcnt(10)
	v_mfma_f32_16x16x32_bf16 v[74:77], v[206:209], v[82:85], v[74:77]
	v_exp_f32_e32 v128, v128
	v_mfma_f32_16x16x32_bf16 v[78:81], v[206:209], v[86:89], v[78:81]
	ds_read_b64_tr_b16 v[206:207], v243 offset:8192
	ds_read_b64_tr_b16 v[208:209], v243 offset:12288
	v_exp_f32_e32 v129, v129
	s_waitcnt lgkmcnt(10)
	v_mfma_f32_16x16x32_bf16 v[18:21], v[210:213], v[98:101], v[18:21]
	v_exp_f32_e32 v130, v130
	v_mfma_f32_16x16x32_bf16 v[22:25], v[210:213], v[102:105], v[22:25]
	ds_read_b64_tr_b16 v[210:211], v244 offset:8192
	ds_read_b64_tr_b16 v[212:213], v244 offset:12288
	v_exp_f32_e32 v131, v131
	s_waitcnt lgkmcnt(10)
	v_mfma_f32_16x16x32_bf16 v[26:29], v[214:217], v[98:101], v[26:29]
	v_exp_f32_e32 v132, v132
	v_mfma_f32_16x16x32_bf16 v[30:33], v[214:217], v[102:105], v[30:33]
	ds_read_b64_tr_b16 v[214:215], v245 offset:8192
	ds_read_b64_tr_b16 v[216:217], v245 offset:12288
	v_exp_f32_e32 v133, v133
	s_waitcnt lgkmcnt(10)
	v_mfma_f32_16x16x32_bf16 v[34:37], v[218:221], v[98:101], v[34:37]
	v_exp_f32_e32 v134, v134
	v_mfma_f32_16x16x32_bf16 v[38:41], v[218:221], v[102:105], v[38:41]
	v_exp_f32_e32 v135, v135
	s_waitcnt lgkmcnt(8)
	v_mfma_f32_16x16x32_bf16 v[42:45], v[222:225], v[98:101], v[42:45]
	v_exp_f32_e32 v136, v136
	v_mfma_f32_16x16x32_bf16 v[46:49], v[222:225], v[102:105], v[46:49]
	v_exp_f32_e32 v137, v137
	s_waitcnt lgkmcnt(6)
	v_mfma_f32_16x16x32_bf16 v[50:53], v[202:205], v[98:101], v[50:53]
	v_exp_f32_e32 v138, v138
	ds_read_b128 v[178:181], v234 offset:32768
	v_mfma_f32_16x16x32_bf16 v[54:57], v[202:205], v[102:105], v[54:57]
	v_exp_f32_e32 v139, v139
	s_waitcnt lgkmcnt(5)
	v_mfma_f32_16x16x32_bf16 v[58:61], v[206:209], v[98:101], v[58:61]
	v_exp_f32_e32 v140, v140
	ds_read_b128 v[182:185], v234 offset:36864
	v_mfma_f32_16x16x32_bf16 v[62:65], v[206:209], v[102:105], v[62:65]
	v_exp_f32_e32 v141, v141
	s_waitcnt lgkmcnt(4)
	v_mfma_f32_16x16x32_bf16 v[66:69], v[210:213], v[98:101], v[66:69]
	v_exp_f32_e32 v142, v142
	ds_read_b128 v[186:189], v234 offset:40960
	v_mfma_f32_16x16x32_bf16 v[70:73], v[210:213], v[102:105], v[70:73]
	v_exp_f32_e32 v143, v143
	s_waitcnt lgkmcnt(3)
	v_mfma_f32_16x16x32_bf16 v[74:77], v[214:217], v[98:101], v[74:77]
	v_exp_f32_e32 v144, v144
	ds_read_b128 v[190:193], v234 offset:45056
	v_mfma_f32_16x16x32_bf16 v[78:81], v[214:217], v[102:105], v[78:81]
	v_exp_f32_e32 v145, v145
	s_waitcnt vmcnt(2)
	s_barrier
; __device__ __forceinline__ void partialSM(f32x16& p0, f32x16& p1, float mC) {
;   (void)mC; (void)p1;
;   for (int r = 0; r < 16; ++r) p0[r] = __builtin_amdgcn_exp2f(p0[r]);
; }
; __device__ __forceinline__ void finishSM(f32x16& p0, f32x16& p1, float& l_reg, bf16x8& pa0, bf16x8& pa1, bf16x8& pa2, bf16x8& pa3) {
;   for (int r = 0; r < 16; ++r) p1[r] = __builtin_amdgcn_exp2f(p1[r]);
;   float ps = 0; for (int r = 0; r < 16; ++r) ps += p0[r]; for (int r = 0; r < 16; ++r) ps += p1[r];
;   { auto rr = __builtin_amdgcn_permlane32_swap(__float_as_uint(ps), __float_as_uint(ps), false, false);
;     ps = __uint_as_float(rr[0]) + __uint_as_float(rr[1]); }
;   l_reg += ps;
;     ...
;   PK4(p0, 0, pa0); PK4(p0, 8, pa1); PK4(p1, 0, pa2); PK4(p1, 8, pa3);
;     ...
; }
; __device__ __forceinline__ void qkt(f32x16& p0, f32x16& p1, const bf16* Ks, const bf16x8* qr, int r32, int hi, const f32x16& negm) {
; #pragma unroll
;   for (int d0 = 0; d0 < 8; ++d0) { int cb = (d0 * 16 + hi * 8) * 2;
;     bf16x8 b0 = *reinterpret_cast<const bf16x8*>((const char*)Ks + KSWZ(r32, cb));
;     bf16x8 b1 = *reinterpret_cast<const bf16x8*>((const char*)Ks + KSWZ(32 + r32, cb));
;     if (d0 == 0) { p0 = __builtin_amdgcn_mfma_f32_32x32x16_bf16(b0, qr[0], negm, 0, 0, 0); p1 = __builtin_amdgcn_mfma_f32_32x32x16_bf16(b1, qr[0], negm, 0, 0, 0); }
;     else { p0 = __builtin_amdgcn_mfma_f32_32x32x16_bf16(b0, qr[d0], p0, 0, 0, 0); p1 = __builtin_amdgcn_mfma_f32_32x32x16_bf16(b1, qr[d0], p1, 0, 0, 0); } }
; }
; __device__ __forceinline__ int v_st(int k, int c) { const int kk = (k & ~0xC) | ((k & 4) << 1) | ((k & 8) >> 1); return ((kk >> 3) * 4 + (c >> 5)) * 512 + ((kk & 7) * 32 + (c & 31)) * 2; }
; __device__ __forceinline__ int v_rd_base(int lane) { return ((lane & 3) << 3) | (((lane >> 2) & 3) << 6) | (((lane >> 4) & 1) << 5) | (((lane >> 5) & 1) << 8); }
; template <int OFF> __device__ __forceinline__ s16x4 tr_read(int vb) {
;   s16x4 r; asm volatile("ds_read_b64_tr_b16 %0, %1 offset:%2" : "=&v"(r) : "v"(vb), "i"(OFF) : "memory"); return r;
; }
; template <typename TQ> ...
;     ...
;   SBAR(); qkt(pB0, pB1, (bf16*)((char*)K_lds + SHM_K), qr, r32, hi, negm);
;   finishSM(pA0, pA1, l_reg, pa0, pa1, pa2, pa3); SBAR();
;   pv_d0(o, vb0, pa0, pa1, pa2, pa3); partialSM(pB0, pB1, mC);
;   __syncthreads();
;   finishSM(pB0, pB1, l_reg, pa0, pa1, pa2, pa3); SBAR();
;   pv_d0(o, vb0 + (int)SHM_V, pa0, pa1, pa2, pa3);
	s_waitcnt lgkmcnt(3)
	v_mfma_f32_16x16x32_bf16 v[82:85], v[178:181], v[146:149], v[2:5]
	v_add_f32_e32 v250, v114, v250
	v_mfma_f32_16x16x32_bf16 v[86:89], v[178:181], v[162:165], v[2:5]
	ds_read_b128 v[178:181], v235 offset:32768
	v_add_f32_e32 v250, v115, v250
	v_add_f32_e32 v250, v116, v250
	s_waitcnt lgkmcnt(3)
	v_mfma_f32_16x16x32_bf16 v[90:93], v[182:185], v[146:149], v[2:5]
	v_add_f32_e32 v250, v117, v250
	v_mfma_f32_16x16x32_bf16 v[94:97], v[182:185], v[162:165], v[2:5]
	ds_read_b128 v[182:185], v235 offset:36864
	v_add_f32_e32 v250, v122, v250
	v_add_f32_e32 v250, v123, v250
	s_waitcnt lgkmcnt(3)
	v_mfma_f32_16x16x32_bf16 v[98:101], v[186:189], v[146:149], v[2:5]
	v_add_f32_e32 v250, v124, v250
	v_mfma_f32_16x16x32_bf16 v[102:105], v[186:189], v[162:165], v[2:5]
	ds_read_b128 v[186:189], v235 offset:40960
	v_add_f32_e32 v250, v125, v250
	v_cvt_pk_bf16_f32 v114, v114, v115
	s_waitcnt lgkmcnt(3)
	v_mfma_f32_16x16x32_bf16 v[106:109], v[190:193], v[146:149], v[2:5]
	v_cvt_pk_bf16_f32 v115, v116, v117
	v_mfma_f32_16x16x32_bf16 v[110:113], v[190:193], v[162:165], v[2:5]
	ds_read_b128 v[190:193], v235 offset:45056
	v_cvt_pk_bf16_f32 v116, v122, v123
	v_cvt_pk_bf16_f32 v117, v124, v125
	s_waitcnt lgkmcnt(3)
	v_mfma_f32_16x16x32_bf16 v[82:85], v[178:181], v[150:153], v[82:85]
	v_add_f32_e32 v251, v118, v251
	v_mfma_f32_16x16x32_bf16 v[86:89], v[178:181], v[166:169], v[86:89]
	ds_read_b128 v[178:181], v236 offset:32768
	v_add_f32_e32 v251, v119, v251
	v_add_f32_e32 v251, v120, v251
	s_waitcnt lgkmcnt(3)
	v_mfma_f32_16x16x32_bf16 v[90:93], v[182:185], v[150:153], v[90:93]
	v_add_f32_e32 v251, v121, v251
	v_mfma_f32_16x16x32_bf16 v[94:97], v[182:185], v[166:169], v[94:97]
	ds_read_b128 v[182:185], v236 offset:36864
	v_add_f32_e32 v251, v126, v251
	v_add_f32_e32 v251, v127, v251
	s_waitcnt lgkmcnt(3)
	v_mfma_f32_16x16x32_bf16 v[98:101], v[186:189], v[150:153], v[98:101]
	v_add_f32_e32 v251, v128, v251
	v_mfma_f32_16x16x32_bf16 v[102:105], v[186:189], v[166:169], v[102:105]
	ds_read_b128 v[186:189], v236 offset:40960
	v_add_f32_e32 v251, v129, v251
	v_cvt_pk_bf16_f32 v118, v118, v119
	s_waitcnt lgkmcnt(3)
	v_mfma_f32_16x16x32_bf16 v[106:109], v[190:193], v[150:153], v[106:109]
	v_cvt_pk_bf16_f32 v119, v120, v121
	v_mfma_f32_16x16x32_bf16 v[110:113], v[190:193], v[166:169], v[110:113]
	ds_read_b128 v[190:193], v236 offset:45056
	v_cvt_pk_bf16_f32 v120, v126, v127
	v_cvt_pk_bf16_f32 v121, v128, v129
	s_waitcnt lgkmcnt(3)
	v_mfma_f32_16x16x32_bf16 v[82:85], v[178:181], v[154:157], v[82:85]
	v_add_f32_e32 v250, v130, v250
	v_mfma_f32_16x16x32_bf16 v[86:89], v[178:181], v[170:173], v[86:89]
	ds_read_b128 v[178:181], v237 offset:32768
	v_add_f32_e32 v250, v131, v250
	v_add_f32_e32 v250, v132, v250
	s_waitcnt lgkmcnt(3)
	v_mfma_f32_16x16x32_bf16 v[90:93], v[182:185], v[154:157], v[90:93]
	v_add_f32_e32 v250, v133, v250
	v_mfma_f32_16x16x32_bf16 v[94:97], v[182:185], v[170:173], v[94:97]
	ds_read_b128 v[182:185], v237 offset:36864
	v_add_f32_e32 v250, v138, v250
	v_add_f32_e32 v250, v139, v250
	s_waitcnt lgkmcnt(3)
	v_mfma_f32_16x16x32_bf16 v[98:101], v[186:189], v[154:157], v[98:101]
	v_add_f32_e32 v250, v140, v250
	ds_read_b64_tr_b16 v[202:203], v238 offset:16384
	ds_read_b64_tr_b16 v[204:205], v238 offset:20480
	v_mfma_f32_16x16x32_bf16 v[102:105], v[186:189], v[170:173], v[102:105]
	ds_read_b128 v[186:189], v237 offset:40960
	v_add_f32_e32 v250, v141, v250
	v_cvt_pk_bf16_f32 v130, v130, v131
	s_waitcnt lgkmcnt(5)
	v_mfma_f32_16x16x32_bf16 v[106:109], v[190:193], v[154:157], v[106:109]
	v_cvt_pk_bf16_f32 v131, v132, v133
	ds_read_b64_tr_b16 v[206:207], v239 offset:16384
	ds_read_b64_tr_b16 v[208:209], v239 offset:20480
	v_mfma_f32_16x16x32_bf16 v[110:113], v[190:193], v[170:173], v[110:113]
	ds_read_b128 v[190:193], v237 offset:45056
	v_cvt_pk_bf16_f32 v132, v138, v139
	v_cvt_pk_bf16_f32 v133, v140, v141
	s_waitcnt lgkmcnt(7)
	v_mfma_f32_16x16x32_bf16 v[82:85], v[178:181], v[158:161], v[82:85]
	v_add_f32_e32 v251, v134, v251
	ds_read_b64_tr_b16 v[210:211], v240 offset:16384
	ds_read_b64_tr_b16 v[212:213], v240 offset:20480
	v_mfma_f32_16x16x32_bf16 v[86:89], v[178:181], v[174:177], v[86:89]
	v_add_f32_e32 v251, v135, v251
	v_add_f32_e32 v251, v136, v251
	s_waitcnt lgkmcnt(8)
	v_mfma_f32_16x16x32_bf16 v[90:93], v[182:185], v[158:161], v[90:93]
	v_add_f32_e32 v251, v137, v251
	ds_read_b64_tr_b16 v[214:215], v241 offset:16384
	ds_read_b64_tr_b16 v[216:217], v241 offset:20480
	v_mfma_f32_16x16x32_bf16 v[94:97], v[182:185], v[174:177], v[94:97]
	v_add_f32_e32 v251, v142, v251
	v_add_f32_e32 v251, v143, v251
	s_waitcnt lgkmcnt(7)
	v_mfma_f32_16x16x32_bf16 v[98:101], v[186:189], v[158:161], v[98:101]
	v_add_f32_e32 v251, v144, v251
	ds_read_b64_tr_b16 v[218:219], v242 offset:16384
	ds_read_b64_tr_b16 v[220:221], v242 offset:20480
	v_mfma_f32_16x16x32_bf16 v[102:105], v[186:189], v[174:177], v[102:105]
	v_add_f32_e32 v251, v145, v251
	v_cvt_pk_bf16_f32 v134, v134, v135
	s_waitcnt lgkmcnt(6)
	v_mfma_f32_16x16x32_bf16 v[106:109], v[190:193], v[158:161], v[106:109]
	v_cvt_pk_bf16_f32 v135, v136, v137
	ds_read_b64_tr_b16 v[222:223], v243 offset:16384
	ds_read_b64_tr_b16 v[224:225], v243 offset:20480
	v_mfma_f32_16x16x32_bf16 v[110:113], v[190:193], v[174:177], v[110:113]
	v_cvt_pk_bf16_f32 v136, v142, v143
	v_cvt_pk_bf16_f32 v137, v144, v145
	v_mfma_f32_16x16x32_bf16 v[18:21], v[202:205], v[114:117], v[18:21]
	v_exp_f32_e32 v82, v82
	v_mfma_f32_16x16x32_bf16 v[22:25], v[202:205], v[118:121], v[22:25]
	ds_read_b64_tr_b16 v[202:203], v244 offset:16384
	ds_read_b64_tr_b16 v[204:205], v244 offset:20480
	v_exp_f32_e32 v83, v83
	v_mfma_f32_16x16x32_bf16 v[26:29], v[206:209], v[114:117], v[26:29]
	v_exp_f32_e32 v84, v84
	v_mfma_f32_16x16x32_bf16 v[30:33], v[206:209], v[118:121], v[30:33]
	ds_read_b64_tr_b16 v[206:207], v245 offset:16384
	ds_read_b64_tr_b16 v[208:209], v245 offset:20480
	v_exp_f32_e32 v85, v85
	s_waitcnt lgkmcnt(10)
; __device__ __forceinline__ void partialSM(f32x16& p0, f32x16& p1, float mC) {
;   (void)mC; (void)p1;
;   for (int r = 0; r < 16; ++r) p0[r] = __builtin_amdgcn_exp2f(p0[r]);
; }
; __device__ __forceinline__ void finishSM(f32x16& p0, f32x16& p1, float& l_reg, bf16x8& pa0, bf16x8& pa1, bf16x8& pa2, bf16x8& pa3) {
;   for (int r = 0; r < 16; ++r) p1[r] = __builtin_amdgcn_exp2f(p1[r]);
;   float ps = 0; for (int r = 0; r < 16; ++r) ps += p0[r]; for (int r = 0; r < 16; ++r) ps += p1[r];
;   { auto rr = __builtin_amdgcn_permlane32_swap(__float_as_uint(ps), __float_as_uint(ps), false, false);
;     ps = __uint_as_float(rr[0]) + __uint_as_float(rr[1]); }
;   l_reg += ps;
;     ...
;   PK4(p0, 0, pa0); PK4(p0, 8, pa1); PK4(p1, 0, pa2); PK4(p1, 8, pa3);
;     ...
; }
; __device__ __forceinline__ void qkt(f32x16& p0, f32x16& p1, const bf16* Ks, const bf16x8* qr, int r32, int hi, const f32x16& negm) {
; #pragma unroll
;   for (int d0 = 0; d0 < 8; ++d0) { int cb = (d0 * 16 + hi * 8) * 2;
;     bf16x8 b0 = *reinterpret_cast<const bf16x8*>((const char*)Ks + KSWZ(r32, cb));
;     bf16x8 b1 = *reinterpret_cast<const bf16x8*>((const char*)Ks + KSWZ(32 + r32, cb));
;     if (d0 == 0) { p0 = __builtin_amdgcn_mfma_f32_32x32x16_bf16(b0, qr[0], negm, 0, 0, 0); p1 = __builtin_amdgcn_mfma_f32_32x32x16_bf16(b1, qr[0], negm, 0, 0, 0); }
;     else { p0 = __builtin_amdgcn_mfma_f32_32x32x16_bf16(b0, qr[d0], p0, 0, 0, 0); p1 = __builtin_amdgcn_mfma_f32_32x32x16_bf16(b1, qr[d0], p1, 0, 0, 0); } }
; }
; __device__ __forceinline__ int v_st(int k, int c) { const int kk = (k & ~0xC) | ((k & 4) << 1) | ((k & 8) >> 1); return ((kk >> 3) * 4 + (c >> 5)) * 512 + ((kk & 7) * 32 + (c & 31)) * 2; }
; __device__ __forceinline__ int v_rd_base(int lane) { return ((lane & 3) << 3) | (((lane >> 2) & 3) << 6) | (((lane >> 4) & 1) << 5) | (((lane >> 5) & 1) << 8); }
; template <int OFF> __device__ __forceinline__ s16x4 tr_read(int vb) {
;   s16x4 r; asm volatile("ds_read_b64_tr_b16 %0, %1 offset:%2" : "=&v"(r) : "v"(vb), "i"(OFF) : "memory"); return r;
; }
; template <typename TQ> ...
;     ...
;   SBAR(); qkt(pB0, pB1, (bf16*)((char*)K_lds + SHM_K), qr, r32, hi, negm);
;   finishSM(pA0, pA1, l_reg, pa0, pa1, pa2, pa3); SBAR();
;   pv_d0(o, vb0, pa0, pa1, pa2, pa3); partialSM(pB0, pB1, mC);
;   __syncthreads();
;   finishSM(pB0, pB1, l_reg, pa0, pa1, pa2, pa3); SBAR();
;   pv_d0(o, vb0 + (int)SHM_V, pa0, pa1, pa2, pa3);
	v_mfma_f32_16x16x32_bf16 v[34:37], v[210:213], v[114:117], v[34:37]
	v_exp_f32_e32 v86, v86
	v_mfma_f32_16x16x32_bf16 v[38:41], v[210:213], v[118:121], v[38:41]
	ds_read_b64_tr_b16 v[210:211], v238 offset:24576
	ds_read_b64_tr_b16 v[212:213], v238 offset:28672
	v_exp_f32_e32 v87, v87
	s_waitcnt lgkmcnt(10)
	v_mfma_f32_16x16x32_bf16 v[42:45], v[214:217], v[114:117], v[42:45]
	v_exp_f32_e32 v88, v88
	v_mfma_f32_16x16x32_bf16 v[46:49], v[214:217], v[118:121], v[46:49]
	ds_read_b64_tr_b16 v[214:215], v239 offset:24576
	ds_read_b64_tr_b16 v[216:217], v239 offset:28672
	v_exp_f32_e32 v89, v89
	s_waitcnt lgkmcnt(10)
	v_mfma_f32_16x16x32_bf16 v[50:53], v[218:221], v[114:117], v[50:53]
	v_exp_f32_e32 v90, v90
	v_mfma_f32_16x16x32_bf16 v[54:57], v[218:221], v[118:121], v[54:57]
	ds_read_b64_tr_b16 v[218:219], v240 offset:24576
	ds_read_b64_tr_b16 v[220:221], v240 offset:28672
	v_exp_f32_e32 v91, v91
	s_waitcnt lgkmcnt(10)
	v_mfma_f32_16x16x32_bf16 v[58:61], v[222:225], v[114:117], v[58:61]
	v_exp_f32_e32 v92, v92
	v_mfma_f32_16x16x32_bf16 v[62:65], v[222:225], v[118:121], v[62:65]
	ds_read_b64_tr_b16 v[222:223], v241 offset:24576
	ds_read_b64_tr_b16 v[224:225], v241 offset:28672
	v_exp_f32_e32 v93, v93
	s_waitcnt lgkmcnt(10)
	v_mfma_f32_16x16x32_bf16 v[66:69], v[202:205], v[114:117], v[66:69]
	v_exp_f32_e32 v94, v94
	v_mfma_f32_16x16x32_bf16 v[70:73], v[202:205], v[118:121], v[70:73]
	ds_read_b64_tr_b16 v[202:203], v242 offset:24576
	ds_read_b64_tr_b16 v[204:205], v242 offset:28672
	v_exp_f32_e32 v95, v95
	s_waitcnt lgkmcnt(10)
	v_mfma_f32_16x16x32_bf16 v[74:77], v[206:209], v[114:117], v[74:77]
	v_exp_f32_e32 v96, v96
	v_mfma_f32_16x16x32_bf16 v[78:81], v[206:209], v[118:121], v[78:81]
	ds_read_b64_tr_b16 v[206:207], v243 offset:24576
	ds_read_b64_tr_b16 v[208:209], v243 offset:28672
	v_exp_f32_e32 v97, v97
	s_waitcnt lgkmcnt(10)
	v_mfma_f32_16x16x32_bf16 v[18:21], v[210:213], v[130:133], v[18:21]
	v_exp_f32_e32 v98, v98
	v_mfma_f32_16x16x32_bf16 v[22:25], v[210:213], v[134:137], v[22:25]
	ds_read_b64_tr_b16 v[210:211], v244 offset:24576
	ds_read_b64_tr_b16 v[212:213], v244 offset:28672
	v_exp_f32_e32 v99, v99
	s_waitcnt lgkmcnt(10)
	v_mfma_f32_16x16x32_bf16 v[26:29], v[214:217], v[130:133], v[26:29]
	v_exp_f32_e32 v100, v100
	v_mfma_f32_16x16x32_bf16 v[30:33], v[214:217], v[134:137], v[30:33]
	ds_read_b64_tr_b16 v[214:215], v245 offset:24576
	ds_read_b64_tr_b16 v[216:217], v245 offset:28672
	v_exp_f32_e32 v101, v101
	s_waitcnt lgkmcnt(10)
	v_mfma_f32_16x16x32_bf16 v[34:37], v[218:221], v[130:133], v[34:37]
	v_exp_f32_e32 v102, v102
	v_mfma_f32_16x16x32_bf16 v[38:41], v[218:221], v[134:137], v[38:41]
	v_exp_f32_e32 v103, v103
	s_waitcnt lgkmcnt(8)
	v_mfma_f32_16x16x32_bf16 v[42:45], v[222:225], v[130:133], v[42:45]
	v_exp_f32_e32 v104, v104
	v_mfma_f32_16x16x32_bf16 v[46:49], v[222:225], v[134:137], v[46:49]
	v_exp_f32_e32 v105, v105
	s_waitcnt lgkmcnt(6)
	v_mfma_f32_16x16x32_bf16 v[50:53], v[202:205], v[130:133], v[50:53]
	v_exp_f32_e32 v106, v106
	ds_read_b128 v[178:181], v234 offset:49152
	v_mfma_f32_16x16x32_bf16 v[54:57], v[202:205], v[134:137], v[54:57]
	v_exp_f32_e32 v107, v107
	s_waitcnt lgkmcnt(5)
	v_mfma_f32_16x16x32_bf16 v[58:61], v[206:209], v[130:133], v[58:61]
	v_exp_f32_e32 v108, v108
	ds_read_b128 v[182:185], v234 offset:53248
	v_mfma_f32_16x16x32_bf16 v[62:65], v[206:209], v[134:137], v[62:65]
	v_exp_f32_e32 v109, v109
	s_waitcnt lgkmcnt(4)
	v_mfma_f32_16x16x32_bf16 v[66:69], v[210:213], v[130:133], v[66:69]
	v_exp_f32_e32 v110, v110
	ds_read_b128 v[186:189], v234 offset:57344
	v_mfma_f32_16x16x32_bf16 v[70:73], v[210:213], v[134:137], v[70:73]
	v_exp_f32_e32 v111, v111
	s_waitcnt lgkmcnt(3)
	v_mfma_f32_16x16x32_bf16 v[74:77], v[214:217], v[130:133], v[74:77]
	v_exp_f32_e32 v112, v112
	ds_read_b128 v[190:193], v234 offset:61440
	v_mfma_f32_16x16x32_bf16 v[78:81], v[214:217], v[134:137], v[78:81]
	v_exp_f32_e32 v113, v113
	s_waitcnt vmcnt(0)
	s_barrier
	s_waitcnt lgkmcnt(3)
	v_mfma_f32_16x16x32_bf16 v[114:117], v[178:181], v[146:149], v[2:5]
	v_add_f32_e32 v250, v82, v250
	v_mfma_f32_16x16x32_bf16 v[118:121], v[178:181], v[162:165], v[2:5]
	ds_read_b128 v[178:181], v235 offset:49152
	v_add_f32_e32 v250, v83, v250
	v_add_f32_e32 v250, v84, v250
	s_waitcnt lgkmcnt(3)
	v_mfma_f32_16x16x32_bf16 v[122:125], v[182:185], v[146:149], v[2:5]
	v_add_f32_e32 v250, v85, v250
	v_mfma_f32_16x16x32_bf16 v[126:129], v[182:185], v[162:165], v[2:5]
	ds_read_b128 v[182:185], v235 offset:53248
	v_add_f32_e32 v250, v90, v250
	v_add_f32_e32 v250, v91, v250
	s_waitcnt lgkmcnt(3)
	v_mfma_f32_16x16x32_bf16 v[130:133], v[186:189], v[146:149], v[2:5]
	v_add_f32_e32 v250, v92, v250
	v_mfma_f32_16x16x32_bf16 v[134:137], v[186:189], v[162:165], v[2:5]
	ds_read_b128 v[186:189], v235 offset:57344
	v_add_f32_e32 v250, v93, v250
	v_cvt_pk_bf16_f32 v82, v82, v83
	s_waitcnt lgkmcnt(3)
	v_mfma_f32_16x16x32_bf16 v[138:141], v[190:193], v[146:149], v[2:5]
	v_cvt_pk_bf16_f32 v83, v84, v85
	v_mfma_f32_16x16x32_bf16 v[142:145], v[190:193], v[162:165], v[2:5]
	ds_read_b128 v[190:193], v235 offset:61440
	v_cvt_pk_bf16_f32 v84, v90, v91
	v_cvt_pk_bf16_f32 v85, v92, v93
	s_waitcnt lgkmcnt(3)
	v_mfma_f32_16x16x32_bf16 v[114:117], v[178:181], v[150:153], v[114:117]
	v_add_f32_e32 v251, v86, v251
	v_mfma_f32_16x16x32_bf16 v[118:121], v[178:181], v[166:169], v[118:121]
	ds_read_b128 v[178:181], v236 offset:49152
	v_add_f32_e32 v251, v87, v251
	v_add_f32_e32 v251, v88, v251
	s_waitcnt lgkmcnt(3)
	v_mfma_f32_16x16x32_bf16 v[122:125], v[182:185], v[150:153], v[122:125]
	v_add_f32_e32 v251, v89, v251
	v_mfma_f32_16x16x32_bf16 v[126:129], v[182:185], v[166:169], v[126:129]
	ds_read_b128 v[182:185], v236 offset:53248
	v_add_f32_e32 v251, v94, v251
	v_add_f32_e32 v251, v95, v251
	s_waitcnt lgkmcnt(3)
; __device__ __forceinline__ void partialSM(f32x16& p0, f32x16& p1, float mC) {
;   (void)mC; (void)p1;
;   for (int r = 0; r < 16; ++r) p0[r] = __builtin_amdgcn_exp2f(p0[r]);
; }
; __device__ __forceinline__ void finishSM(f32x16& p0, f32x16& p1, float& l_reg, bf16x8& pa0, bf16x8& pa1, bf16x8& pa2, bf16x8& pa3) {
;   for (int r = 0; r < 16; ++r) p1[r] = __builtin_amdgcn_exp2f(p1[r]);
;   float ps = 0; for (int r = 0; r < 16; ++r) ps += p0[r]; for (int r = 0; r < 16; ++r) ps += p1[r];
;   { auto rr = __builtin_amdgcn_permlane32_swap(__float_as_uint(ps), __float_as_uint(ps), false, false);
;     ps = __uint_as_float(rr[0]) + __uint_as_float(rr[1]); }
;   l_reg += ps;
;     ...
;   PK4(p0, 0, pa0); PK4(p0, 8, pa1); PK4(p1, 0, pa2); PK4(p1, 8, pa3);
;     ...
; }
; __device__ __forceinline__ void qkt(f32x16& p0, f32x16& p1, const bf16* Ks, const bf16x8* qr, int r32, int hi, const f32x16& negm) {
; #pragma unroll
;   for (int d0 = 0; d0 < 8; ++d0) { int cb = (d0 * 16 + hi * 8) * 2;
;     bf16x8 b0 = *reinterpret_cast<const bf16x8*>((const char*)Ks + KSWZ(r32, cb));
;     bf16x8 b1 = *reinterpret_cast<const bf16x8*>((const char*)Ks + KSWZ(32 + r32, cb));
;     if (d0 == 0) { p0 = __builtin_amdgcn_mfma_f32_32x32x16_bf16(b0, qr[0], negm, 0, 0, 0); p1 = __builtin_amdgcn_mfma_f32_32x32x16_bf16(b1, qr[0], negm, 0, 0, 0); }
;     else { p0 = __builtin_amdgcn_mfma_f32_32x32x16_bf16(b0, qr[d0], p0, 0, 0, 0); p1 = __builtin_amdgcn_mfma_f32_32x32x16_bf16(b1, qr[d0], p1, 0, 0, 0); } }
; }
; __device__ __forceinline__ int v_st(int k, int c) { const int kk = (k & ~0xC) | ((k & 4) << 1) | ((k & 8) >> 1); return ((kk >> 3) * 4 + (c >> 5)) * 512 + ((kk & 7) * 32 + (c & 31)) * 2; }
; __device__ __forceinline__ int v_rd_base(int lane) { return ((lane & 3) << 3) | (((lane >> 2) & 3) << 6) | (((lane >> 4) & 1) << 5) | (((lane >> 5) & 1) << 8); }
; template <int OFF> __device__ __forceinline__ s16x4 tr_read(int vb) {
;   s16x4 r; asm volatile("ds_read_b64_tr_b16 %0, %1 offset:%2" : "=&v"(r) : "v"(vb), "i"(OFF) : "memory"); return r;
; }
; template <typename TQ> ...
;     ...
;   SBAR(); qkt(pB0, pB1, (bf16*)((char*)K_lds + SHM_K), qr, r32, hi, negm);
;   finishSM(pA0, pA1, l_reg, pa0, pa1, pa2, pa3); SBAR();
;   pv_d0(o, vb0, pa0, pa1, pa2, pa3); partialSM(pB0, pB1, mC);
;   __syncthreads();
;   finishSM(pB0, pB1, l_reg, pa0, pa1, pa2, pa3); SBAR();
;   pv_d0(o, vb0 + (int)SHM_V, pa0, pa1, pa2, pa3);
	v_mfma_f32_16x16x32_bf16 v[130:133], v[186:189], v[150:153], v[130:133]
	v_add_f32_e32 v251, v96, v251
	v_mfma_f32_16x16x32_bf16 v[134:137], v[186:189], v[166:169], v[134:137]
	ds_read_b128 v[186:189], v236 offset:57344
	v_add_f32_e32 v251, v97, v251
	v_cvt_pk_bf16_f32 v86, v86, v87
	s_waitcnt lgkmcnt(3)
	v_mfma_f32_16x16x32_bf16 v[138:141], v[190:193], v[150:153], v[138:141]
	v_cvt_pk_bf16_f32 v87, v88, v89
	v_mfma_f32_16x16x32_bf16 v[142:145], v[190:193], v[166:169], v[142:145]
	ds_read_b128 v[190:193], v236 offset:61440
	v_cvt_pk_bf16_f32 v88, v94, v95
	v_cvt_pk_bf16_f32 v89, v96, v97
	s_waitcnt lgkmcnt(3)
	v_mfma_f32_16x16x32_bf16 v[114:117], v[178:181], v[154:157], v[114:117]
	v_add_f32_e32 v250, v98, v250
	v_mfma_f32_16x16x32_bf16 v[118:121], v[178:181], v[170:173], v[118:121]
	ds_read_b128 v[178:181], v237 offset:49152
	v_add_f32_e32 v250, v99, v250
	v_add_f32_e32 v250, v100, v250
	s_waitcnt lgkmcnt(3)
	v_mfma_f32_16x16x32_bf16 v[122:125], v[182:185], v[154:157], v[122:125]
	v_add_f32_e32 v250, v101, v250
	v_mfma_f32_16x16x32_bf16 v[126:129], v[182:185], v[170:173], v[126:129]
	ds_read_b128 v[182:185], v237 offset:53248
	v_add_f32_e32 v250, v106, v250
	v_add_f32_e32 v250, v107, v250
	s_waitcnt lgkmcnt(3)
	v_mfma_f32_16x16x32_bf16 v[130:133], v[186:189], v[154:157], v[130:133]
	v_add_f32_e32 v250, v108, v250
	ds_read_b64_tr_b16 v[202:203], v238 offset:32768
	ds_read_b64_tr_b16 v[204:205], v238 offset:36864
	v_mfma_f32_16x16x32_bf16 v[134:137], v[186:189], v[170:173], v[134:137]
	ds_read_b128 v[186:189], v237 offset:57344
	v_add_f32_e32 v250, v109, v250
	v_cvt_pk_bf16_f32 v98, v98, v99
	s_waitcnt lgkmcnt(5)
	v_mfma_f32_16x16x32_bf16 v[138:141], v[190:193], v[154:157], v[138:141]
	v_cvt_pk_bf16_f32 v99, v100, v101
	ds_read_b64_tr_b16 v[206:207], v239 offset:32768
	ds_read_b64_tr_b16 v[208:209], v239 offset:36864
	v_mfma_f32_16x16x32_bf16 v[142:145], v[190:193], v[170:173], v[142:145]
	ds_read_b128 v[190:193], v237 offset:61440
	v_cvt_pk_bf16_f32 v100, v106, v107
	v_cvt_pk_bf16_f32 v101, v108, v109
	s_waitcnt lgkmcnt(7)
	v_mfma_f32_16x16x32_bf16 v[114:117], v[178:181], v[158:161], v[114:117]
	v_add_f32_e32 v251, v102, v251
	ds_read_b64_tr_b16 v[210:211], v240 offset:32768
	ds_read_b64_tr_b16 v[212:213], v240 offset:36864
	v_mfma_f32_16x16x32_bf16 v[118:121], v[178:181], v[174:177], v[118:121]
	v_add_f32_e32 v251, v103, v251
	v_add_f32_e32 v251, v104, v251
	s_waitcnt lgkmcnt(8)
	v_mfma_f32_16x16x32_bf16 v[122:125], v[182:185], v[158:161], v[122:125]
	v_add_f32_e32 v251, v105, v251
	ds_read_b64_tr_b16 v[214:215], v241 offset:32768
	ds_read_b64_tr_b16 v[216:217], v241 offset:36864
	v_mfma_f32_16x16x32_bf16 v[126:129], v[182:185], v[174:177], v[126:129]
	v_add_f32_e32 v251, v110, v251
	v_add_f32_e32 v251, v111, v251
	s_waitcnt lgkmcnt(7)
	v_mfma_f32_16x16x32_bf16 v[130:133], v[186:189], v[158:161], v[130:133]
	v_add_f32_e32 v251, v112, v251
	ds_read_b64_tr_b16 v[218:219], v242 offset:32768
	ds_read_b64_tr_b16 v[220:221], v242 offset:36864
	v_mfma_f32_16x16x32_bf16 v[134:137], v[186:189], v[174:177], v[134:137]
	v_add_f32_e32 v251, v113, v251
	v_cvt_pk_bf16_f32 v102, v102, v103
	s_waitcnt lgkmcnt(6)
	v_mfma_f32_16x16x32_bf16 v[138:141], v[190:193], v[158:161], v[138:141]
	v_cvt_pk_bf16_f32 v103, v104, v105
	ds_read_b64_tr_b16 v[222:223], v243 offset:32768
	ds_read_b64_tr_b16 v[224:225], v243 offset:36864
	v_mfma_f32_16x16x32_bf16 v[142:145], v[190:193], v[174:177], v[142:145]
	v_cvt_pk_bf16_f32 v104, v110, v111
	v_cvt_pk_bf16_f32 v105, v112, v113
	v_mfma_f32_16x16x32_bf16 v[18:21], v[202:205], v[82:85], v[18:21]
	v_exp_f32_e32 v114, v114
	v_mfma_f32_16x16x32_bf16 v[22:25], v[202:205], v[86:89], v[22:25]
	ds_read_b64_tr_b16 v[202:203], v244 offset:32768
	ds_read_b64_tr_b16 v[204:205], v244 offset:36864
	v_exp_f32_e32 v115, v115
	v_mfma_f32_16x16x32_bf16 v[26:29], v[206:209], v[82:85], v[26:29]
	v_exp_f32_e32 v116, v116
	v_mfma_f32_16x16x32_bf16 v[30:33], v[206:209], v[86:89], v[30:33]
	ds_read_b64_tr_b16 v[206:207], v245 offset:32768
	ds_read_b64_tr_b16 v[208:209], v245 offset:36864
	v_exp_f32_e32 v117, v117
	s_waitcnt lgkmcnt(10)
	v_mfma_f32_16x16x32_bf16 v[34:37], v[210:213], v[82:85], v[34:37]
	v_exp_f32_e32 v118, v118
	v_mfma_f32_16x16x32_bf16 v[38:41], v[210:213], v[86:89], v[38:41]
	ds_read_b64_tr_b16 v[210:211], v238 offset:40960
	ds_read_b64_tr_b16 v[212:213], v238 offset:45056
	v_exp_f32_e32 v119, v119
	s_waitcnt lgkmcnt(10)
	v_mfma_f32_16x16x32_bf16 v[42:45], v[214:217], v[82:85], v[42:45]
	v_exp_f32_e32 v120, v120
	v_mfma_f32_16x16x32_bf16 v[46:49], v[214:217], v[86:89], v[46:49]
	ds_read_b64_tr_b16 v[214:215], v239 offset:40960
	ds_read_b64_tr_b16 v[216:217], v239 offset:45056
	v_exp_f32_e32 v121, v121
	s_waitcnt lgkmcnt(10)
	v_mfma_f32_16x16x32_bf16 v[50:53], v[218:221], v[82:85], v[50:53]
	v_exp_f32_e32 v122, v122
	v_mfma_f32_16x16x32_bf16 v[54:57], v[218:221], v[86:89], v[54:57]
	ds_read_b64_tr_b16 v[218:219], v240 offset:40960
	ds_read_b64_tr_b16 v[220:221], v240 offset:45056
	v_exp_f32_e32 v123, v123
	s_waitcnt lgkmcnt(10)
	v_mfma_f32_16x16x32_bf16 v[58:61], v[222:225], v[82:85], v[58:61]
	v_exp_f32_e32 v124, v124
	v_mfma_f32_16x16x32_bf16 v[62:65], v[222:225], v[86:89], v[62:65]
	ds_read_b64_tr_b16 v[222:223], v241 offset:40960
	ds_read_b64_tr_b16 v[224:225], v241 offset:45056
	v_exp_f32_e32 v125, v125
	s_waitcnt lgkmcnt(10)
	v_mfma_f32_16x16x32_bf16 v[66:69], v[202:205], v[82:85], v[66:69]
	v_exp_f32_e32 v126, v126
	v_mfma_f32_16x16x32_bf16 v[70:73], v[202:205], v[86:89], v[70:73]
	ds_read_b64_tr_b16 v[202:203], v242 offset:40960
	ds_read_b64_tr_b16 v[204:205], v242 offset:45056
	v_exp_f32_e32 v127, v127
	s_waitcnt lgkmcnt(10)
; #define SBAR() __builtin_amdgcn_sched_barrier(0)
; __device__ __forceinline__ void finishSM(f32x16& p0, f32x16& p1, float& l_reg, bf16x8& pa0, bf16x8& pa1, bf16x8& pa2, bf16x8& pa3) {
;   for (int r = 0; r < 16; ++r) p1[r] = __builtin_amdgcn_exp2f(p1[r]);
;   float ps = 0; for (int r = 0; r < 16; ++r) ps += p0[r]; for (int r = 0; r < 16; ++r) ps += p1[r];
;   { auto rr = __builtin_amdgcn_permlane32_swap(__float_as_uint(ps), __float_as_uint(ps), false, false);
;     ps = __uint_as_float(rr[0]) + __uint_as_float(rr[1]); }
;   l_reg += ps;
;     ...
;   PK4(p0, 0, pa0); PK4(p0, 8, pa1); PK4(p1, 0, pa2); PK4(p1, 8, pa3);
;     ...
; }
; __device__ __forceinline__ void qkt(f32x16& p0, f32x16& p1, const bf16* Ks, const bf16x8* qr, int r32, int hi, const f32x16& negm) {
; #pragma unroll
;   for (int d0 = 0; d0 < 8; ++d0) { int cb = (d0 * 16 + hi * 8) * 2;
;     bf16x8 b0 = *reinterpret_cast<const bf16x8*>((const char*)Ks + KSWZ(r32, cb));
;     bf16x8 b1 = *reinterpret_cast<const bf16x8*>((const char*)Ks + KSWZ(32 + r32, cb));
;     if (d0 == 0) { p0 = __builtin_amdgcn_mfma_f32_32x32x16_bf16(b0, qr[0], negm, 0, 0, 0); p1 = __builtin_amdgcn_mfma_f32_32x32x16_bf16(b1, qr[0], negm, 0, 0, 0); }
;     else { p0 = __builtin_amdgcn_mfma_f32_32x32x16_bf16(b0, qr[d0], p0, 0, 0, 0); p1 = __builtin_amdgcn_mfma_f32_32x32x16_bf16(b1, qr[d0], p1, 0, 0, 0); } }
; }
; __device__ __forceinline__ int v_st(int k, int c) { const int kk = (k & ~0xC) | ((k & 4) << 1) | ((k & 8) >> 1); return ((kk >> 3) * 4 + (c >> 5)) * 512 + ((kk & 7) * 32 + (c & 31)) * 2; }
; __device__ __forceinline__ int v_rd_base(int lane) { return ((lane & 3) << 3) | (((lane >> 2) & 3) << 6) | (((lane >> 4) & 1) << 5) | (((lane >> 5) & 1) << 8); }
; template <int OFF> __device__ __forceinline__ s16x4 tr_read(int vb) {
;   s16x4 r; asm volatile("ds_read_b64_tr_b16 %0, %1 offset:%2" : "=&v"(r) : "v"(vb), "i"(OFF) : "memory"); return r;
; }
; template <int D0> __device__ __forceinline__ void pv_one(f32x16& od, int vb, bf16x8 pa0, bf16x8 pa1, bf16x8 pa2, bf16x8 pa3) {
; template <typename TQ> ...
;     ...
;   SBAR(); qkt(pB0, pB1, (bf16*)((char*)K_lds + SHM_K), qr, r32, hi, negm);
;   finishSM(pA0, pA1, l_reg, pa0, pa1, pa2, pa3); SBAR();
;   pv_d0(o, vb0, pa0, pa1, pa2, pa3); partialSM(pB0, pB1, mC);
;   __syncthreads();
;   finishSM(pB0, pB1, l_reg, pa0, pa1, pa2, pa3); SBAR();
;   pv_d0(o, vb0 + (int)SHM_V, pa0, pa1, pa2, pa3);
	v_mfma_f32_16x16x32_bf16 v[74:77], v[206:209], v[82:85], v[74:77]
	v_exp_f32_e32 v128, v128
	v_mfma_f32_16x16x32_bf16 v[78:81], v[206:209], v[86:89], v[78:81]
	ds_read_b64_tr_b16 v[206:207], v243 offset:40960
	ds_read_b64_tr_b16 v[208:209], v243 offset:45056
	v_exp_f32_e32 v129, v129
	s_waitcnt lgkmcnt(10)
	v_mfma_f32_16x16x32_bf16 v[18:21], v[210:213], v[98:101], v[18:21]
	v_exp_f32_e32 v130, v130
	v_mfma_f32_16x16x32_bf16 v[22:25], v[210:213], v[102:105], v[22:25]
	ds_read_b64_tr_b16 v[210:211], v244 offset:40960
	ds_read_b64_tr_b16 v[212:213], v244 offset:45056
	v_exp_f32_e32 v131, v131
	s_waitcnt lgkmcnt(10)
	v_mfma_f32_16x16x32_bf16 v[26:29], v[214:217], v[98:101], v[26:29]
	v_exp_f32_e32 v132, v132
	v_mfma_f32_16x16x32_bf16 v[30:33], v[214:217], v[102:105], v[30:33]
	ds_read_b64_tr_b16 v[214:215], v245 offset:40960
	ds_read_b64_tr_b16 v[216:217], v245 offset:45056
	v_exp_f32_e32 v133, v133
	s_waitcnt lgkmcnt(10)
	v_mfma_f32_16x16x32_bf16 v[34:37], v[218:221], v[98:101], v[34:37]
	v_exp_f32_e32 v134, v134
	v_mfma_f32_16x16x32_bf16 v[38:41], v[218:221], v[102:105], v[38:41]
	v_exp_f32_e32 v135, v135
	s_waitcnt lgkmcnt(8)
	v_mfma_f32_16x16x32_bf16 v[42:45], v[222:225], v[98:101], v[42:45]
	v_exp_f32_e32 v136, v136
	v_mfma_f32_16x16x32_bf16 v[46:49], v[222:225], v[102:105], v[46:49]
	v_exp_f32_e32 v137, v137
	s_waitcnt lgkmcnt(6)
	v_mfma_f32_16x16x32_bf16 v[50:53], v[202:205], v[98:101], v[50:53]
	v_exp_f32_e32 v138, v138
	v_mfma_f32_16x16x32_bf16 v[54:57], v[202:205], v[102:105], v[54:57]
	v_exp_f32_e32 v139, v139
	s_waitcnt lgkmcnt(4)
	v_mfma_f32_16x16x32_bf16 v[58:61], v[206:209], v[98:101], v[58:61]
	v_exp_f32_e32 v140, v140
	v_mfma_f32_16x16x32_bf16 v[62:65], v[206:209], v[102:105], v[62:65]
	v_exp_f32_e32 v141, v141
	s_waitcnt lgkmcnt(2)
	v_mfma_f32_16x16x32_bf16 v[66:69], v[210:213], v[98:101], v[66:69]
	v_exp_f32_e32 v142, v142
	v_mfma_f32_16x16x32_bf16 v[70:73], v[210:213], v[102:105], v[70:73]
	v_exp_f32_e32 v143, v143
	s_waitcnt lgkmcnt(0)
	v_mfma_f32_16x16x32_bf16 v[74:77], v[214:217], v[98:101], v[74:77]
	v_exp_f32_e32 v144, v144
	v_mfma_f32_16x16x32_bf16 v[78:81], v[214:217], v[102:105], v[78:81]
	v_exp_f32_e32 v145, v145
	s_waitcnt vmcnt(0)
	v_add_f32_e32 v250, v114, v250
	v_add_f32_e32 v250, v115, v250
	v_add_f32_e32 v250, v116, v250
	v_add_f32_e32 v250, v117, v250
	v_add_f32_e32 v250, v122, v250
	v_add_f32_e32 v250, v123, v250
	v_add_f32_e32 v250, v124, v250
	v_add_f32_e32 v250, v125, v250
	v_cvt_pk_bf16_f32 v114, v114, v115
	v_cvt_pk_bf16_f32 v115, v116, v117
	v_cvt_pk_bf16_f32 v116, v122, v123
	v_cvt_pk_bf16_f32 v117, v124, v125
	v_add_f32_e32 v251, v118, v251
	v_add_f32_e32 v251, v119, v251
	v_add_f32_e32 v251, v120, v251
	v_add_f32_e32 v251, v121, v251
	v_add_f32_e32 v251, v126, v251
	v_add_f32_e32 v251, v127, v251
	v_add_f32_e32 v251, v128, v251
	v_add_f32_e32 v251, v129, v251
	v_cvt_pk_bf16_f32 v118, v118, v119
	v_cvt_pk_bf16_f32 v119, v120, v121
	v_cvt_pk_bf16_f32 v120, v126, v127
	v_cvt_pk_bf16_f32 v121, v128, v129
	v_add_f32_e32 v250, v130, v250
	v_add_f32_e32 v250, v131, v250
	v_add_f32_e32 v250, v132, v250
	v_add_f32_e32 v250, v133, v250
	v_add_f32_e32 v250, v138, v250
	v_add_f32_e32 v250, v139, v250
	v_add_f32_e32 v250, v140, v250
	v_add_f32_e32 v250, v141, v250
	v_cvt_pk_bf16_f32 v130, v130, v131
	v_cvt_pk_bf16_f32 v131, v132, v133
	v_cvt_pk_bf16_f32 v132, v138, v139
	v_cvt_pk_bf16_f32 v133, v140, v141
	v_add_f32_e32 v251, v134, v251
	v_add_f32_e32 v251, v135, v251
	v_add_f32_e32 v251, v136, v251
	v_add_f32_e32 v251, v137, v251
	v_add_f32_e32 v251, v142, v251
	v_add_f32_e32 v251, v143, v251
	v_add_f32_e32 v251, v144, v251
	v_add_f32_e32 v251, v145, v251
	v_cvt_pk_bf16_f32 v134, v134, v135
	v_cvt_pk_bf16_f32 v135, v136, v137
	v_cvt_pk_bf16_f32 v136, v142, v143
	v_cvt_pk_bf16_f32 v137, v144, v145
	ds_read_b64_tr_b16 v[202:203], v238 offset:49152
	ds_read_b64_tr_b16 v[204:205], v238 offset:53248
	ds_read_b64_tr_b16 v[206:207], v239 offset:49152
	ds_read_b64_tr_b16 v[208:209], v239 offset:53248
	ds_read_b64_tr_b16 v[210:211], v240 offset:49152
	ds_read_b64_tr_b16 v[212:213], v240 offset:53248
	ds_read_b64_tr_b16 v[214:215], v241 offset:49152
	ds_read_b64_tr_b16 v[216:217], v241 offset:53248
	ds_read_b64_tr_b16 v[218:219], v242 offset:49152
	ds_read_b64_tr_b16 v[220:221], v242 offset:53248
	ds_read_b64_tr_b16 v[222:223], v243 offset:49152
	ds_read_b64_tr_b16 v[224:225], v243 offset:53248
	s_waitcnt lgkmcnt(10)
	v_mfma_f32_16x16x32_bf16 v[18:21], v[202:205], v[114:117], v[18:21]
	v_mfma_f32_16x16x32_bf16 v[22:25], v[202:205], v[118:121], v[22:25]
	ds_read_b64_tr_b16 v[202:203], v244 offset:49152
	ds_read_b64_tr_b16 v[204:205], v244 offset:53248
	s_waitcnt lgkmcnt(10)
	v_mfma_f32_16x16x32_bf16 v[26:29], v[206:209], v[114:117], v[26:29]
	v_mfma_f32_16x16x32_bf16 v[30:33], v[206:209], v[118:121], v[30:33]
	ds_read_b64_tr_b16 v[206:207], v245 offset:49152
	ds_read_b64_tr_b16 v[208:209], v245 offset:53248
	s_waitcnt lgkmcnt(10)
	v_mfma_f32_16x16x32_bf16 v[34:37], v[210:213], v[114:117], v[34:37]
	v_mfma_f32_16x16x32_bf16 v[38:41], v[210:213], v[118:121], v[38:41]
	ds_read_b64_tr_b16 v[210:211], v238 offset:57344
	ds_read_b64_tr_b16 v[212:213], v238 offset:61440
	s_waitcnt lgkmcnt(10)
	v_mfma_f32_16x16x32_bf16 v[42:45], v[214:217], v[114:117], v[42:45]
	v_mfma_f32_16x16x32_bf16 v[46:49], v[214:217], v[118:121], v[46:49]
	ds_read_b64_tr_b16 v[214:215], v239 offset:57344
	ds_read_b64_tr_b16 v[216:217], v239 offset:61440
	s_waitcnt lgkmcnt(10)
	v_mfma_f32_16x16x32_bf16 v[50:53], v[218:221], v[114:117], v[50:53]
	v_mfma_f32_16x16x32_bf16 v[54:57], v[218:221], v[118:121], v[54:57]
	ds_read_b64_tr_b16 v[218:219], v240 offset:57344
	ds_read_b64_tr_b16 v[220:221], v240 offset:61440
	s_waitcnt lgkmcnt(10)
; #define SBAR() __builtin_amdgcn_sched_barrier(0)
; __device__ __forceinline__ int crow(int r, int hi) { return (r & 3) + 8 * (r >> 2) + 4 * hi; }
; template <typename TQ> ...
;     ...
;   finishSM(pB0, pB1, l_reg, pa0, pa1, pa2, pa3); SBAR();
;   pv_d0(o, vb0 + (int)SHM_V, pa0, pa1, pa2, pa3);
;   if (hi == 0) li_l[r32] = l_reg; asm volatile("s_waitcnt lgkmcnt(0)" ::: "memory");
;   float rli[16];
; #pragma unroll
;   for (int r = 0; r < 16; ++r) rli[r] = __builtin_amdgcn_rcpf(li_l[crow(r, hi)]);
;   int le = (int)(threadIdx.x & 63u); asm volatile("" : "+v"(le));
;   const int r32e = le & 31, hie = le >> 5;
;   bf16* Ow = Ob + (long)(wid * QBLK) * LDO;
; #pragma unroll
;   for (int r = 0; r < 16; ++r) { int orow = crow(r, hie);
;     for (int d0 = 0; d0 < 4; ++d0) Ow[(long)orow * LDO + d0 * 32 + r32e] = __float2bfloat16(o[d0][r] * rli[r]); }
; __global__ void __launch_bounds__(NTHR, 2) fwd_megakernel(KArgs a) {
;     ...
;         for (int i = 0; i < upb; ++i) {
;             const int unit = vcu * upb + i; if (unit >= 512) break;
;             const int grp = unit >> 7, rem = unit & 127, gq = rem >> 5, qb = rem & 31, b = grp >> 1, kvh = grp & 1, h = kvh * 4 + gq;
;             const size_t qoff = ((size_t)(b * SEQ + qb * 256)) * DM + h * 128, koff = (size_t)b * SKV * 256 + kvh * 128;
;             att::attn_dense_body<att::bf16>(Q + qoff, Kb + koff, Vb + koff, O + qoff, SKV, (char*)lds_raw, mC, a.g_q, (const float*)(ws + WS_ROPE), (const float*)(ws + WS_ROPE) + 4096, qb * 256);
;             __syncthreads();
;         }
	v_mfma_f32_16x16x32_bf16 v[58:61], v[222:225], v[114:117], v[58:61]
	v_mfma_f32_16x16x32_bf16 v[62:65], v[222:225], v[118:121], v[62:65]
	ds_read_b64_tr_b16 v[222:223], v241 offset:57344
	ds_read_b64_tr_b16 v[224:225], v241 offset:61440
	s_waitcnt lgkmcnt(10)
	v_mfma_f32_16x16x32_bf16 v[66:69], v[202:205], v[114:117], v[66:69]
	v_mfma_f32_16x16x32_bf16 v[70:73], v[202:205], v[118:121], v[70:73]
	ds_read_b64_tr_b16 v[202:203], v242 offset:57344
	ds_read_b64_tr_b16 v[204:205], v242 offset:61440
	s_waitcnt lgkmcnt(10)
	v_mfma_f32_16x16x32_bf16 v[74:77], v[206:209], v[114:117], v[74:77]
	v_mfma_f32_16x16x32_bf16 v[78:81], v[206:209], v[118:121], v[78:81]
	ds_read_b64_tr_b16 v[206:207], v243 offset:57344
	ds_read_b64_tr_b16 v[208:209], v243 offset:61440
	s_waitcnt lgkmcnt(10)
	v_mfma_f32_16x16x32_bf16 v[18:21], v[210:213], v[130:133], v[18:21]
	v_mfma_f32_16x16x32_bf16 v[22:25], v[210:213], v[134:137], v[22:25]
	ds_read_b64_tr_b16 v[210:211], v244 offset:57344
	ds_read_b64_tr_b16 v[212:213], v244 offset:61440
	s_waitcnt lgkmcnt(10)
	v_mfma_f32_16x16x32_bf16 v[26:29], v[214:217], v[130:133], v[26:29]
	v_mfma_f32_16x16x32_bf16 v[30:33], v[214:217], v[134:137], v[30:33]
	ds_read_b64_tr_b16 v[214:215], v245 offset:57344
	ds_read_b64_tr_b16 v[216:217], v245 offset:61440
	s_waitcnt lgkmcnt(10)
	v_mfma_f32_16x16x32_bf16 v[34:37], v[218:221], v[130:133], v[34:37]
	v_mfma_f32_16x16x32_bf16 v[38:41], v[218:221], v[134:137], v[38:41]
	s_waitcnt lgkmcnt(8)
	v_mfma_f32_16x16x32_bf16 v[42:45], v[222:225], v[130:133], v[42:45]
	v_mfma_f32_16x16x32_bf16 v[46:49], v[222:225], v[134:137], v[46:49]
	s_waitcnt lgkmcnt(6)
	v_mfma_f32_16x16x32_bf16 v[50:53], v[202:205], v[130:133], v[50:53]
	v_mfma_f32_16x16x32_bf16 v[54:57], v[202:205], v[134:137], v[54:57]
	s_waitcnt lgkmcnt(4)
	v_mfma_f32_16x16x32_bf16 v[58:61], v[206:209], v[130:133], v[58:61]
	v_mfma_f32_16x16x32_bf16 v[62:65], v[206:209], v[134:137], v[62:65]
	s_waitcnt lgkmcnt(2)
	v_mfma_f32_16x16x32_bf16 v[66:69], v[210:213], v[130:133], v[66:69]
	v_mfma_f32_16x16x32_bf16 v[70:73], v[210:213], v[134:137], v[70:73]
	s_waitcnt lgkmcnt(0)
	v_mfma_f32_16x16x32_bf16 v[74:77], v[214:217], v[130:133], v[74:77]
	v_mfma_f32_16x16x32_bf16 v[78:81], v[214:217], v[134:137], v[78:81]
	s_setprio 0
	ds_swizzle_b32 v6, v250 offset:swizzle(SWAP,16)
	s_waitcnt lgkmcnt(0)
	v_add_f32_e32 v250, v250, v6
	v_mov_b32_e32 v6, v250
	s_nop 1
	v_permlane32_swap_b32_e32 v250, v6
	v_add_f32_e32 v250, v250, v6
	v_rcp_f32_e32 v250, v250
	ds_swizzle_b32 v6, v251 offset:swizzle(SWAP,16)
	s_waitcnt lgkmcnt(0)
	v_add_f32_e32 v251, v251, v6
	v_mov_b32_e32 v6, v251
	s_nop 1
	v_permlane32_swap_b32_e32 v251, v6
	v_add_f32_e32 v251, v251, v6
	v_rcp_f32_e32 v251, v251
	s_add_u32 s12, s71, s48
	s_addc_u32 s13, s72, s49
	v_add_u32_e32 v201, s52, v16
	v_lshlrev_b32_e32 v201, 11, v201
	v_lshl_or_b32 v7, v17, 3, v201
	v_add_u32_e32 v200, 0x8000, v7
	v_mul_f32_e32 v18, v18, v250
	v_mul_f32_e32 v19, v19, v250
	v_mul_f32_e32 v20, v20, v250
	v_mul_f32_e32 v21, v21, v250
	v_cvt_pk_bf16_f32 v18, v18, v19
	v_cvt_pk_bf16_f32 v19, v20, v21
	global_store_dwordx2 v7, v[18:19], s[12:13] offset:0
	v_mul_f32_e32 v22, v22, v251
	v_mul_f32_e32 v23, v23, v251
	v_mul_f32_e32 v24, v24, v251
	v_mul_f32_e32 v25, v25, v251
	v_cvt_pk_bf16_f32 v22, v22, v23
	v_cvt_pk_bf16_f32 v23, v24, v25
	global_store_dwordx2 v200, v[22:23], s[12:13] offset:0
	v_mul_f32_e32 v26, v26, v250
	v_mul_f32_e32 v27, v27, v250
	v_mul_f32_e32 v28, v28, v250
	v_mul_f32_e32 v29, v29, v250
	v_cvt_pk_bf16_f32 v26, v26, v27
	v_cvt_pk_bf16_f32 v27, v28, v29
	global_store_dwordx2 v7, v[26:27], s[12:13] offset:32
	v_mul_f32_e32 v30, v30, v251
	v_mul_f32_e32 v31, v31, v251
	v_mul_f32_e32 v32, v32, v251
	v_mul_f32_e32 v33, v33, v251
	v_cvt_pk_bf16_f32 v30, v30, v31
	v_cvt_pk_bf16_f32 v31, v32, v33
	global_store_dwordx2 v200, v[30:31], s[12:13] offset:32
	v_mul_f32_e32 v34, v34, v250
	v_mul_f32_e32 v35, v35, v250
	v_mul_f32_e32 v36, v36, v250
	v_mul_f32_e32 v37, v37, v250
	v_cvt_pk_bf16_f32 v34, v34, v35
	v_cvt_pk_bf16_f32 v35, v36, v37
	global_store_dwordx2 v7, v[34:35], s[12:13] offset:64
	v_mul_f32_e32 v38, v38, v251
	v_mul_f32_e32 v39, v39, v251
	v_mul_f32_e32 v40, v40, v251
	v_mul_f32_e32 v41, v41, v251
	v_cvt_pk_bf16_f32 v38, v38, v39
	v_cvt_pk_bf16_f32 v39, v40, v41
	global_store_dwordx2 v200, v[38:39], s[12:13] offset:64
	v_mul_f32_e32 v42, v42, v250
	v_mul_f32_e32 v43, v43, v250
	v_mul_f32_e32 v44, v44, v250
	v_mul_f32_e32 v45, v45, v250
	v_cvt_pk_bf16_f32 v42, v42, v43
	v_cvt_pk_bf16_f32 v43, v44, v45
	global_store_dwordx2 v7, v[42:43], s[12:13] offset:96
	v_mul_f32_e32 v46, v46, v251
	v_mul_f32_e32 v47, v47, v251
	v_mul_f32_e32 v48, v48, v251
	v_mul_f32_e32 v49, v49, v251
	v_cvt_pk_bf16_f32 v46, v46, v47
	v_cvt_pk_bf16_f32 v47, v48, v49
	global_store_dwordx2 v200, v[46:47], s[12:13] offset:96
	v_mul_f32_e32 v50, v50, v250
	v_mul_f32_e32 v51, v51, v250
	v_mul_f32_e32 v52, v52, v250
	v_mul_f32_e32 v53, v53, v250
	v_cvt_pk_bf16_f32 v50, v50, v51
	v_cvt_pk_bf16_f32 v51, v52, v53
	global_store_dwordx2 v7, v[50:51], s[12:13] offset:128
	v_mul_f32_e32 v54, v54, v251
	v_mul_f32_e32 v55, v55, v251
	v_mul_f32_e32 v56, v56, v251
	v_mul_f32_e32 v57, v57, v251
	v_cvt_pk_bf16_f32 v54, v54, v55
	v_cvt_pk_bf16_f32 v55, v56, v57
	global_store_dwordx2 v200, v[54:55], s[12:13] offset:128
	v_mul_f32_e32 v58, v58, v250
	v_mul_f32_e32 v59, v59, v250
	v_mul_f32_e32 v60, v60, v250
	v_mul_f32_e32 v61, v61, v250
	v_cvt_pk_bf16_f32 v58, v58, v59
	v_cvt_pk_bf16_f32 v59, v60, v61
	global_store_dwordx2 v7, v[58:59], s[12:13] offset:160
	v_mul_f32_e32 v62, v62, v251
	v_mul_f32_e32 v63, v63, v251
	v_mul_f32_e32 v64, v64, v251
	v_mul_f32_e32 v65, v65, v251
	v_cvt_pk_bf16_f32 v62, v62, v63
	v_cvt_pk_bf16_f32 v63, v64, v65
	global_store_dwordx2 v200, v[62:63], s[12:13] offset:160
	v_mul_f32_e32 v66, v66, v250
	v_mul_f32_e32 v67, v67, v250
	v_mul_f32_e32 v68, v68, v250
	v_mul_f32_e32 v69, v69, v250
	v_cvt_pk_bf16_f32 v66, v66, v67
	v_cvt_pk_bf16_f32 v67, v68, v69
	global_store_dwordx2 v7, v[66:67], s[12:13] offset:192
	v_mul_f32_e32 v70, v70, v251
	v_mul_f32_e32 v71, v71, v251
	v_mul_f32_e32 v72, v72, v251
	v_mul_f32_e32 v73, v73, v251
	v_cvt_pk_bf16_f32 v70, v70, v71
	v_cvt_pk_bf16_f32 v71, v72, v73
	global_store_dwordx2 v200, v[70:71], s[12:13] offset:192
	v_mul_f32_e32 v74, v74, v250
	v_mul_f32_e32 v75, v75, v250
	v_mul_f32_e32 v76, v76, v250
	v_mul_f32_e32 v77, v77, v250
	v_cvt_pk_bf16_f32 v74, v74, v75
	v_cvt_pk_bf16_f32 v75, v76, v77
	global_store_dwordx2 v7, v[74:75], s[12:13] offset:224
	v_mul_f32_e32 v78, v78, v251
	v_mul_f32_e32 v79, v79, v251
	v_mul_f32_e32 v80, v80, v251
	v_mul_f32_e32 v81, v81, v251
	v_cvt_pk_bf16_f32 v78, v78, v79
	v_cvt_pk_bf16_f32 v79, v80, v81
	global_store_dwordx2 v200, v[78:79], s[12:13] offset:224
	s_add_i32 s74, s74, 1
	s_add_i32 s94, s94, 1
	s_cmp_eq_u32 s74, s66
	s_cselect_b64 s[0:1], -1, 0
	s_barrier
	s_branch .LBB0_818
